# scan: parameter/fragment LDS reads of the next block issued earlier (inside the gate math / before the conv)
# baseline (speedup 1.0000x reference)
.Lscan1_sub:
	s_mov_b64 s[62:63], s[44:45]
	global_load_dword v82, v233, s[62:63]
	s_add_u32 s62, s62, 0x1800
	s_addc_u32 s63, s63, 0
	global_load_dword v83, v233, s[62:63]
	s_add_u32 s62, s62, 0x1800
	s_addc_u32 s63, s63, 0
	global_load_dword v84, v233, s[62:63]
	s_add_u32 s62, s62, 0x1800
	s_addc_u32 s63, s63, 0
	global_load_dword v85, v233, s[62:63]
	s_add_u32 s62, s62, 0x1800
	s_addc_u32 s63, s63, 0
	global_load_dword v86, v233, s[62:63]
	s_add_u32 s62, s62, 0x1800
	s_addc_u32 s63, s63, 0
	global_load_dword v87, v233, s[62:63]
	s_add_u32 s62, s62, 0x1800
	s_addc_u32 s63, s63, 0
	global_load_dword v88, v233, s[62:63]
	s_add_u32 s62, s62, 0x1800
	s_addc_u32 s63, s63, 0
	global_load_dword v89, v233, s[62:63]
	s_add_u32 s62, s62, 0x1800
	s_addc_u32 s63, s63, 0
	global_load_dword v90, v233, s[62:63]
	s_add_u32 s62, s62, 0x1800
	s_addc_u32 s63, s63, 0
	global_load_dword v91, v233, s[62:63]
	s_add_u32 s62, s62, 0x1800
	s_addc_u32 s63, s63, 0
	global_load_dword v92, v233, s[62:63]
	s_add_u32 s62, s62, 0x1800
	s_addc_u32 s63, s63, 0
	global_load_dword v93, v233, s[62:63]
	s_add_u32 s62, s62, 0x1800
	s_addc_u32 s63, s63, 0
	global_load_dword v94, v233, s[62:63]
	s_add_u32 s62, s62, 0x1800
	s_addc_u32 s63, s63, 0
	global_load_dword v95, v233, s[62:63]
	s_add_u32 s62, s62, 0x1800
	s_addc_u32 s63, s63, 0
	global_load_dword v96, v233, s[62:63]
	s_add_u32 s62, s62, 0x1800
	s_addc_u32 s63, s63, 0
	global_load_dword v97, v233, s[62:63]
	s_add_u32 s62, s62, 0x1800
	s_addc_u32 s63, s63, 0
	s_mov_b64 s[44:45], s[62:63]
	ds_read_b128 v[110:113], v229 offset:0
	ds_read_b128 v[122:125], v229 offset:19968
	ds_read_b128 v[114:117], v229 offset:64
	ds_read_b128 v[126:129], v229 offset:20032
	ds_read_b128 v[118:121], v229 offset:128
	ds_read_b128 v[130:133], v229 offset:20096
	ds_read_b128 v[150:153], v230
	ds_read_b128 v[154:157], v230 offset:384
	ds_read_b128 v[158:161], v230 offset:768
	s_mov_b32 s62, -1
	s_mov_b32 s63, 0xffff
	s_mov_b64 exec, s[62:63]
	v_lshlrev_b32_e32 v64, 16, v66
	v_and_b32_e32 v65, 0xffff0000, v66
	v_fma_f32 v242, v58, v48, v56
	v_fma_f32 v243, v59, v49, v57
	v_lshlrev_b32_e32 v58, 16, v67
	v_and_b32_e32 v59, 0xffff0000, v67
	v_fma_f32 v244, v60, v48, v56
	v_fma_f32 v245, v61, v49, v57
	v_fma_f32 v242, v60, v50, v242
	v_fma_f32 v243, v61, v51, v243
	v_fma_f32 v244, v62, v50, v244
	v_fma_f32 v245, v63, v51, v245
	v_fma_f32 v242, v62, v52, v242
	v_fma_f32 v243, v63, v53, v243
	v_fma_f32 v244, v64, v52, v244
	v_fma_f32 v245, v65, v53, v245
	v_fma_f32 v242, v64, v54, v242
	v_fma_f32 v243, v65, v55, v243
	v_fma_f32 v244, v58, v54, v244
	v_fma_f32 v245, v59, v55, v245
	ds_write_b64 v226, v[242:243] offset:0
	v_cvt_pk_bf16_f32 v246, v242, v243
	ds_write_b64 v226, v[244:245] offset:400
	v_cvt_pk_bf16_f32 v247, v244, v245
	ds_write_b32 v227, v246 offset:0
	ds_write_b32 v227, v247 offset:208
	v_lshlrev_b32_e32 v60, 16, v68
	v_and_b32_e32 v61, 0xffff0000, v68
	v_fma_f32 v242, v62, v48, v56
	v_fma_f32 v243, v63, v49, v57
	v_lshlrev_b32_e32 v62, 16, v69
	v_and_b32_e32 v63, 0xffff0000, v69
	v_fma_f32 v244, v64, v48, v56
	v_fma_f32 v245, v65, v49, v57
	v_fma_f32 v242, v64, v50, v242
	v_fma_f32 v243, v65, v51, v243
	v_fma_f32 v244, v58, v50, v244
	v_fma_f32 v245, v59, v51, v245
	v_fma_f32 v242, v58, v52, v242
	v_fma_f32 v243, v59, v53, v243
	v_fma_f32 v244, v60, v52, v244
	v_fma_f32 v245, v61, v53, v245
	v_fma_f32 v242, v60, v54, v242
	v_fma_f32 v243, v61, v55, v243
	v_fma_f32 v244, v62, v54, v244
	v_fma_f32 v245, v63, v55, v245
	ds_write_b64 v226, v[242:243] offset:800
	v_cvt_pk_bf16_f32 v246, v242, v243
	ds_write_b64 v226, v[244:245] offset:1200
	v_cvt_pk_bf16_f32 v247, v244, v245
	ds_write_b32 v227, v246 offset:416
	ds_write_b32 v227, v247 offset:624
	v_lshlrev_b32_e32 v64, 16, v70
	v_and_b32_e32 v65, 0xffff0000, v70
	v_fma_f32 v242, v58, v48, v56
	v_fma_f32 v243, v59, v49, v57
	v_lshlrev_b32_e32 v58, 16, v71
	v_and_b32_e32 v59, 0xffff0000, v71
	v_fma_f32 v244, v60, v48, v56
	v_fma_f32 v245, v61, v49, v57
	v_fma_f32 v242, v60, v50, v242
	v_fma_f32 v243, v61, v51, v243
	v_fma_f32 v244, v62, v50, v244
	v_fma_f32 v245, v63, v51, v245
	v_fma_f32 v242, v62, v52, v242
	v_fma_f32 v243, v63, v53, v243
	v_fma_f32 v244, v64, v52, v244
	v_fma_f32 v245, v65, v53, v245
	v_fma_f32 v242, v64, v54, v242
	v_fma_f32 v243, v65, v55, v243
	v_fma_f32 v244, v58, v54, v244
	v_fma_f32 v245, v59, v55, v245
	ds_write_b64 v226, v[242:243] offset:1600
	v_cvt_pk_bf16_f32 v246, v242, v243
	ds_write_b64 v226, v[244:245] offset:2000
	v_cvt_pk_bf16_f32 v247, v244, v245
	ds_write_b32 v227, v246 offset:832
	ds_write_b32 v227, v247 offset:1040
	v_lshlrev_b32_e32 v60, 16, v72
	v_and_b32_e32 v61, 0xffff0000, v72
	v_fma_f32 v242, v62, v48, v56
	v_fma_f32 v243, v63, v49, v57
	v_lshlrev_b32_e32 v62, 16, v73
	v_and_b32_e32 v63, 0xffff0000, v73
	v_fma_f32 v244, v64, v48, v56
	v_fma_f32 v245, v65, v49, v57
	v_fma_f32 v242, v64, v50, v242
	v_fma_f32 v243, v65, v51, v243
	v_fma_f32 v244, v58, v50, v244
	v_fma_f32 v245, v59, v51, v245
	v_fma_f32 v242, v58, v52, v242
	v_fma_f32 v243, v59, v53, v243
	v_fma_f32 v244, v60, v52, v244
	v_fma_f32 v245, v61, v53, v245
	v_fma_f32 v242, v60, v54, v242
	v_fma_f32 v243, v61, v55, v243
	v_fma_f32 v244, v62, v54, v244
	v_fma_f32 v245, v63, v55, v245
	ds_write_b64 v226, v[242:243] offset:2400
	v_cvt_pk_bf16_f32 v246, v242, v243
	ds_write_b64 v226, v[244:245] offset:2800
	v_cvt_pk_bf16_f32 v247, v244, v245
	ds_write_b32 v227, v246 offset:1248
	ds_write_b32 v227, v247 offset:1456
	v_lshlrev_b32_e32 v64, 16, v74
	v_and_b32_e32 v65, 0xffff0000, v74
	v_fma_f32 v242, v58, v48, v56
	v_fma_f32 v243, v59, v49, v57
	v_lshlrev_b32_e32 v58, 16, v75
	v_and_b32_e32 v59, 0xffff0000, v75
	v_fma_f32 v244, v60, v48, v56
	v_fma_f32 v245, v61, v49, v57
	v_fma_f32 v242, v60, v50, v242
	v_fma_f32 v243, v61, v51, v243
	v_fma_f32 v244, v62, v50, v244
	v_fma_f32 v245, v63, v51, v245
	v_fma_f32 v242, v62, v52, v242
	v_fma_f32 v243, v63, v53, v243
	v_fma_f32 v244, v64, v52, v244
	v_fma_f32 v245, v65, v53, v245
	v_fma_f32 v242, v64, v54, v242
	v_fma_f32 v243, v65, v55, v243
	v_fma_f32 v244, v58, v54, v244
	v_fma_f32 v245, v59, v55, v245
	ds_write_b64 v226, v[242:243] offset:3200
	v_cvt_pk_bf16_f32 v246, v242, v243
	ds_write_b64 v226, v[244:245] offset:3600
	v_cvt_pk_bf16_f32 v247, v244, v245
	ds_write_b32 v227, v246 offset:1664
	ds_write_b32 v227, v247 offset:1872
	v_lshlrev_b32_e32 v60, 16, v76
	v_and_b32_e32 v61, 0xffff0000, v76
	v_fma_f32 v242, v62, v48, v56
	v_fma_f32 v243, v63, v49, v57
	v_lshlrev_b32_e32 v62, 16, v77
	v_and_b32_e32 v63, 0xffff0000, v77
	v_fma_f32 v244, v64, v48, v56
	v_fma_f32 v245, v65, v49, v57
	v_fma_f32 v242, v64, v50, v242
	v_fma_f32 v243, v65, v51, v243
	v_fma_f32 v244, v58, v50, v244
	v_fma_f32 v245, v59, v51, v245
	v_fma_f32 v242, v58, v52, v242
	v_fma_f32 v243, v59, v53, v243
	v_fma_f32 v244, v60, v52, v244
	v_fma_f32 v245, v61, v53, v245
	v_fma_f32 v242, v60, v54, v242
	v_fma_f32 v243, v61, v55, v243
	v_fma_f32 v244, v62, v54, v244
	v_fma_f32 v245, v63, v55, v245
	ds_write_b64 v226, v[242:243] offset:4000
	v_cvt_pk_bf16_f32 v246, v242, v243
	ds_write_b64 v226, v[244:245] offset:4400
	v_cvt_pk_bf16_f32 v247, v244, v245
	ds_write_b32 v227, v246 offset:2080
	ds_write_b32 v227, v247 offset:2288
	v_lshlrev_b32_e32 v64, 16, v78
	v_and_b32_e32 v65, 0xffff0000, v78
	v_fma_f32 v242, v58, v48, v56
	v_fma_f32 v243, v59, v49, v57
	v_lshlrev_b32_e32 v58, 16, v79
	v_and_b32_e32 v59, 0xffff0000, v79
	v_fma_f32 v244, v60, v48, v56
	v_fma_f32 v245, v61, v49, v57
	v_fma_f32 v242, v60, v50, v242
	v_fma_f32 v243, v61, v51, v243
	v_fma_f32 v244, v62, v50, v244
	v_fma_f32 v245, v63, v51, v245
	v_fma_f32 v242, v62, v52, v242
	v_fma_f32 v243, v63, v53, v243
	v_fma_f32 v244, v64, v52, v244
	v_fma_f32 v245, v65, v53, v245
	v_fma_f32 v242, v64, v54, v242
	v_fma_f32 v243, v65, v55, v243
	v_fma_f32 v244, v58, v54, v244
	v_fma_f32 v245, v59, v55, v245
	ds_write_b64 v226, v[242:243] offset:4800
	v_cvt_pk_bf16_f32 v246, v242, v243
	ds_write_b64 v226, v[244:245] offset:5200
	v_cvt_pk_bf16_f32 v247, v244, v245
	ds_write_b32 v227, v246 offset:2496
	ds_write_b32 v227, v247 offset:2704
	v_lshlrev_b32_e32 v60, 16, v80
	v_and_b32_e32 v61, 0xffff0000, v80
	v_fma_f32 v242, v62, v48, v56
	v_fma_f32 v243, v63, v49, v57
	v_lshlrev_b32_e32 v62, 16, v81
	v_and_b32_e32 v63, 0xffff0000, v81
	v_fma_f32 v244, v64, v48, v56
	v_fma_f32 v245, v65, v49, v57
	v_fma_f32 v242, v64, v50, v242
	v_fma_f32 v243, v65, v51, v243
	v_fma_f32 v244, v58, v50, v244
	v_fma_f32 v245, v59, v51, v245
	v_fma_f32 v242, v58, v52, v242
	v_fma_f32 v243, v59, v53, v243
	v_fma_f32 v244, v60, v52, v244
	v_fma_f32 v245, v61, v53, v245
	v_fma_f32 v242, v60, v54, v242
	v_fma_f32 v243, v61, v55, v243
	v_fma_f32 v244, v62, v54, v244
	v_fma_f32 v245, v63, v55, v245
	ds_write_b64 v226, v[242:243] offset:5600
	v_cvt_pk_bf16_f32 v246, v242, v243
	ds_write_b64 v226, v[244:245] offset:6000
	v_cvt_pk_bf16_f32 v247, v244, v245
	ds_write_b32 v227, v246 offset:2912
	ds_write_b32 v227, v247 offset:3120
	s_mov_b64 exec, -1
	s_waitcnt lgkmcnt(0)
	ds_read_b128 v[98:101], v228 offset:0
	ds_read_b128 v[102:105], v228 offset:64
	ds_read_b128 v[106:109], v228 offset:128
	ds_read_b128 v[162:165], v231
	s_waitcnt lgkmcnt(0)
	v_mfma_f32_16x16x32_bf16 v[134:137], v[110:113], v[98:101], 0
	v_mfma_f32_16x16x32_bf16 v[138:141], v[122:125], v[98:101], 0
	v_mfma_f32_16x16x32_bf16 v[134:137], v[114:117], v[102:105], v[134:137]
	v_mfma_f32_16x16x32_bf16 v[138:141], v[126:129], v[102:105], v[138:141]
	v_mfma_f32_16x16x32_bf16 v[134:137], v[118:121], v[106:109], v[134:137]
	v_mfma_f32_16x16x32_bf16 v[138:141], v[130:133], v[106:109], v[138:141]
	ds_read_b128 v[110:113], v229 offset:3328
	ds_read_b128 v[122:125], v229 offset:23296
	ds_read_b128 v[114:117], v229 offset:3392
	ds_read_b128 v[126:129], v229 offset:23360
	ds_read_b128 v[118:121], v229 offset:3456
	ds_read_b128 v[130:133], v229 offset:23424
	s_nop 7
	s_nop 7
	v_fmamk_f32 v166, v134, 0xbfb8aa3b, v150
	v_fmamk_f32 v204, v135, 0xbfb8aa3b, v151
	v_fmamk_f32 v210, v136, 0xbfb8aa3b, v152
	v_fmamk_f32 v216, v137, 0xbfb8aa3b, v153
	v_fmamk_f32 v167, v138, 0xbfb8aa3b, v154
	v_fmamk_f32 v205, v139, 0xbfb8aa3b, v155
	v_fmamk_f32 v211, v140, 0xbfb8aa3b, v156
	v_fmamk_f32 v217, v141, 0xbfb8aa3b, v157
	v_exp_f32_e32 v166, v166
	v_exp_f32_e32 v204, v204
	v_exp_f32_e32 v210, v210
	v_exp_f32_e32 v216, v216
	v_exp_f32_e32 v167, v167
	v_exp_f32_e32 v205, v205
	v_exp_f32_e32 v211, v211
	v_exp_f32_e32 v217, v217
	v_add_f32_e32 v166, 1.0, v166
	v_add_f32_e32 v204, 1.0, v204
	v_add_f32_e32 v210, 1.0, v210
	v_add_f32_e32 v216, 1.0, v216
	v_add_f32_e32 v167, 1.0, v167
	v_add_f32_e32 v205, 1.0, v205
	v_add_f32_e32 v211, 1.0, v211
	v_add_f32_e32 v217, 1.0, v217
	v_rcp_f32_e32 v166, v166
	v_rcp_f32_e32 v204, v204
	v_rcp_f32_e32 v210, v210
	v_rcp_f32_e32 v216, v216
	v_rcp_f32_e32 v167, v167
	v_rcp_f32_e32 v205, v205
	v_rcp_f32_e32 v211, v211
	v_rcp_f32_e32 v217, v217
	v_mul_f32_e32 v168, v158, v166
	v_mul_f32_e32 v206, v159, v204
	v_mul_f32_e32 v212, v160, v210
	v_mul_f32_e32 v218, v161, v216
	v_mul_f32_e32 v167, v162, v167
	v_mul_f32_e32 v205, v163, v205
	v_mul_f32_e32 v211, v164, v211
	v_mul_f32_e32 v217, v165, v217
	ds_read_b128 v[150:153], v230 offset:64
	ds_read_b128 v[154:157], v230 offset:448
	ds_read_b128 v[158:161], v230 offset:832
	ds_read_b128 v[162:165], v231 offset:64
	v_exp_f32_e32 v166, v168
	v_exp_f32_e32 v204, v206
	v_exp_f32_e32 v210, v212
	v_exp_f32_e32 v216, v218
	v_fmaak_f32 v170, v168, v248, 0xbe1d955b
	v_fmaak_f32 v208, v206, v248, 0xbe1d955b
	v_fmaak_f32 v214, v212, v248, 0xbe1d955b
	v_fmaak_f32 v220, v218, v248, 0xbe1d955b
	v_fmaak_f32 v170, v168, v170, 0xbee35847
	v_fmaak_f32 v208, v206, v208, 0xbee35847
	v_fmaak_f32 v214, v212, v214, 0xbee35847
	v_fmaak_f32 v220, v218, v220, 0xbee35847
	v_min3_f32 v169, v168, v206, v212
	v_fmaak_f32 v170, v168, v170, 0xbf75fdf0
	v_fmaak_f32 v208, v206, v208, 0xbf75fdf0
	v_fmaak_f32 v214, v212, v214, 0xbf75fdf0
	v_fmaak_f32 v220, v218, v220, 0xbf75fdf0
	v_min_f32_e32 v169, v169, v218
	v_fmaak_f32 v170, v168, v170, 0xbfb17218
	v_fmaak_f32 v208, v206, v208, 0xbfb17218
	v_fmaak_f32 v214, v212, v214, 0xbfb17218
	v_fmaak_f32 v220, v218, v220, 0xbfb17218
	v_cmp_nlt_f32_e32 vcc, 0xbe38aa3b, v169
	v_mul_f32_e32 v170, v170, v168
	v_mul_f32_e32 v208, v208, v206
	v_mul_f32_e32 v214, v214, v212
	v_mul_f32_e32 v220, v220, v218
	s_cbranch_vccnz .Lscan1_far0
.Lscan1_back0:
	v_sqrt_f32_e32 v170, v170
	v_sqrt_f32_e32 v208, v208
	v_sqrt_f32_e32 v214, v214
	v_sqrt_f32_e32 v220, v220
	v_mul_f32_e32 v167, v167, v170
	v_mul_f32_e32 v205, v205, v208
	v_mul_f32_e32 v211, v211, v214
	v_mul_f32_e32 v217, v217, v220
	s_waitcnt lgkmcnt(0)
	v_mfma_f32_16x16x32_bf16 v[142:145], v[110:113], v[98:101], 0
	v_mfma_f32_16x16x32_bf16 v[146:149], v[122:125], v[98:101], 0
	v_mfma_f32_16x16x32_bf16 v[142:145], v[114:117], v[102:105], v[142:145]
	v_mfma_f32_16x16x32_bf16 v[146:149], v[126:129], v[102:105], v[146:149]
	v_mfma_f32_16x16x32_bf16 v[142:145], v[118:121], v[106:109], v[142:145]
	v_mfma_f32_16x16x32_bf16 v[146:149], v[130:133], v[106:109], v[146:149]
	v_fmac_f32_dpp v167, v167, v166 row_shr:1 row_mask:0xf bank_mask:0xf bound_ctrl:1
	v_fmac_f32_dpp v205, v205, v204 row_shr:1 row_mask:0xf bank_mask:0xf bound_ctrl:1
	v_fmac_f32_dpp v211, v211, v210 row_shr:1 row_mask:0xf bank_mask:0xf bound_ctrl:1
	v_fmac_f32_dpp v217, v217, v216 row_shr:1 row_mask:0xf bank_mask:0xf bound_ctrl:1
	v_mul_f32_dpp v166, v166, v166 row_shr:1 row_mask:0xf bank_mask:0xf
	v_mul_f32_dpp v204, v204, v204 row_shr:1 row_mask:0xf bank_mask:0xf
	v_mul_f32_dpp v210, v210, v210 row_shr:1 row_mask:0xf bank_mask:0xf
	v_mul_f32_dpp v216, v216, v216 row_shr:1 row_mask:0xf bank_mask:0xf
	v_fmac_f32_dpp v167, v167, v166 row_shr:2 row_mask:0xf bank_mask:0xf bound_ctrl:1
	v_fmac_f32_dpp v205, v205, v204 row_shr:2 row_mask:0xf bank_mask:0xf bound_ctrl:1
	v_fmac_f32_dpp v211, v211, v210 row_shr:2 row_mask:0xf bank_mask:0xf bound_ctrl:1
	v_fmac_f32_dpp v217, v217, v216 row_shr:2 row_mask:0xf bank_mask:0xf bound_ctrl:1
	v_mul_f32_dpp v166, v166, v166 row_shr:2 row_mask:0xf bank_mask:0xf
	v_mul_f32_dpp v204, v204, v204 row_shr:2 row_mask:0xf bank_mask:0xf
	v_mul_f32_dpp v210, v210, v210 row_shr:2 row_mask:0xf bank_mask:0xf
	v_mul_f32_dpp v216, v216, v216 row_shr:2 row_mask:0xf bank_mask:0xf
	v_fmac_f32_dpp v167, v167, v166 row_shr:4 row_mask:0xf bank_mask:0xf bound_ctrl:1
	v_fmac_f32_dpp v205, v205, v204 row_shr:4 row_mask:0xf bank_mask:0xf bound_ctrl:1
	v_fmac_f32_dpp v211, v211, v210 row_shr:4 row_mask:0xf bank_mask:0xf bound_ctrl:1
	v_fmac_f32_dpp v217, v217, v216 row_shr:4 row_mask:0xf bank_mask:0xf bound_ctrl:1
	v_mul_f32_dpp v166, v166, v166 row_shr:4 row_mask:0xf bank_mask:0xf
	v_mul_f32_dpp v204, v204, v204 row_shr:4 row_mask:0xf bank_mask:0xf
	v_mul_f32_dpp v210, v210, v210 row_shr:4 row_mask:0xf bank_mask:0xf
	v_mul_f32_dpp v216, v216, v216 row_shr:4 row_mask:0xf bank_mask:0xf
	v_fmac_f32_dpp v167, v167, v166 row_shr:8 row_mask:0xf bank_mask:0xf bound_ctrl:1
	v_fmac_f32_dpp v205, v205, v204 row_shr:8 row_mask:0xf bank_mask:0xf bound_ctrl:1
	v_fmac_f32_dpp v211, v211, v210 row_shr:8 row_mask:0xf bank_mask:0xf bound_ctrl:1
	v_fmac_f32_dpp v217, v217, v216 row_shr:8 row_mask:0xf bank_mask:0xf bound_ctrl:1
	v_mul_f32_dpp v166, v166, v166 row_shr:8 row_mask:0xf bank_mask:0xf
	v_mul_f32_dpp v204, v204, v204 row_shr:8 row_mask:0xf bank_mask:0xf
	v_mul_f32_dpp v210, v210, v210 row_shr:8 row_mask:0xf bank_mask:0xf
	v_mul_f32_dpp v216, v216, v216 row_shr:8 row_mask:0xf bank_mask:0xf
	v_fma_f32 v168, v166, v0, v167
	v_fma_f32 v206, v204, v1, v205
	v_fma_f32 v212, v210, v2, v211
	v_fma_f32 v218, v216, v3, v217
	ds_bpermute_b32 v0, v232, v168
	ds_bpermute_b32 v1, v232, v206
	ds_bpermute_b32 v2, v232, v212
	ds_bpermute_b32 v3, v232, v218
	ds_bpermute_b32 v222, v232, v166
	ds_bpermute_b32 v223, v232, v204
	ds_bpermute_b32 v224, v232, v210
	ds_bpermute_b32 v225, v232, v216
	ds_read_b128 v[110:113], v229 offset:6656
	ds_read_b128 v[122:125], v229 offset:26624
	ds_read_b128 v[114:117], v229 offset:6720
	ds_read_b128 v[126:129], v229 offset:26688
	ds_read_b128 v[118:121], v229 offset:6784
	ds_read_b128 v[130:133], v229 offset:26752
	v_fmamk_f32 v166, v142, 0xbfb8aa3b, v150
	v_fmamk_f32 v204, v143, 0xbfb8aa3b, v151
	v_fmamk_f32 v210, v144, 0xbfb8aa3b, v152
	v_fmamk_f32 v216, v145, 0xbfb8aa3b, v153
	v_fmamk_f32 v167, v146, 0xbfb8aa3b, v154
	v_fmamk_f32 v205, v147, 0xbfb8aa3b, v155
	v_fmamk_f32 v211, v148, 0xbfb8aa3b, v156
	v_fmamk_f32 v217, v149, 0xbfb8aa3b, v157
	v_exp_f32_e32 v166, v166
	v_exp_f32_e32 v204, v204
	v_exp_f32_e32 v210, v210
	v_exp_f32_e32 v216, v216
	v_exp_f32_e32 v167, v167
	v_exp_f32_e32 v205, v205
	v_exp_f32_e32 v211, v211
	v_exp_f32_e32 v217, v217
	v_add_f32_e32 v166, 1.0, v166
	v_add_f32_e32 v204, 1.0, v204
	v_add_f32_e32 v210, 1.0, v210
	v_add_f32_e32 v216, 1.0, v216
	v_add_f32_e32 v167, 1.0, v167
	v_add_f32_e32 v205, 1.0, v205
	v_add_f32_e32 v211, 1.0, v211
	v_add_f32_e32 v217, 1.0, v217
	v_rcp_f32_e32 v166, v166
	v_rcp_f32_e32 v204, v204
	v_rcp_f32_e32 v210, v210
	v_rcp_f32_e32 v216, v216
	v_rcp_f32_e32 v167, v167
	v_rcp_f32_e32 v205, v205
	v_rcp_f32_e32 v211, v211
	v_rcp_f32_e32 v217, v217
	v_mul_f32_e32 v168, v158, v166
	v_mul_f32_e32 v206, v159, v204
	v_mul_f32_e32 v212, v160, v210
	v_mul_f32_e32 v218, v161, v216
	v_mul_f32_e32 v167, v162, v167
	v_mul_f32_e32 v205, v163, v205
	v_mul_f32_e32 v211, v164, v211
	v_mul_f32_e32 v217, v165, v217
	ds_read_b128 v[150:153], v230 offset:128
	ds_read_b128 v[154:157], v230 offset:512
	ds_read_b128 v[158:161], v230 offset:896
	ds_read_b128 v[162:165], v231 offset:128
	v_exp_f32_e32 v166, v168
	v_exp_f32_e32 v204, v206
	v_exp_f32_e32 v210, v212
	v_exp_f32_e32 v216, v218
	v_fmaak_f32 v170, v168, v248, 0xbe1d955b
	v_fmaak_f32 v208, v206, v248, 0xbe1d955b
	v_fmaak_f32 v214, v212, v248, 0xbe1d955b
	v_fmaak_f32 v220, v218, v248, 0xbe1d955b
	v_fmaak_f32 v170, v168, v170, 0xbee35847
	v_fmaak_f32 v208, v206, v208, 0xbee35847
	v_fmaak_f32 v214, v212, v214, 0xbee35847
	v_fmaak_f32 v220, v218, v220, 0xbee35847
	v_min3_f32 v169, v168, v206, v212
	v_fmaak_f32 v170, v168, v170, 0xbf75fdf0
	v_fmaak_f32 v208, v206, v208, 0xbf75fdf0
	v_fmaak_f32 v214, v212, v214, 0xbf75fdf0
	v_fmaak_f32 v220, v218, v220, 0xbf75fdf0
	v_min_f32_e32 v169, v169, v218
	v_fmaak_f32 v170, v168, v170, 0xbfb17218
	v_fmaak_f32 v208, v206, v208, 0xbfb17218
	v_fmaak_f32 v214, v212, v214, 0xbfb17218
	v_fmaak_f32 v220, v218, v220, 0xbfb17218
	v_cmp_nlt_f32_e32 vcc, 0xbe38aa3b, v169
	v_mul_f32_e32 v170, v170, v168
	v_mul_f32_e32 v208, v208, v206
	v_mul_f32_e32 v214, v214, v212
	v_mul_f32_e32 v220, v220, v218
	s_cbranch_vccnz .Lscan1_far1
.Lscan1_back1:
	v_sqrt_f32_e32 v170, v170
	v_sqrt_f32_e32 v208, v208
	v_sqrt_f32_e32 v214, v214
	v_sqrt_f32_e32 v220, v220
	v_mul_f32_e32 v167, v167, v170
	v_mul_f32_e32 v205, v205, v208
	v_mul_f32_e32 v211, v211, v214
	v_mul_f32_e32 v217, v217, v220
	s_waitcnt lgkmcnt(0)
	v_mul_f32_e32 v24, v24, v222
	v_mul_f32_e32 v25, v25, v223
	v_mul_f32_e32 v26, v26, v224
	v_mul_f32_e32 v27, v27, v225
	v_mfma_f32_16x16x32_bf16 v[134:137], v[110:113], v[98:101], 0
	v_mfma_f32_16x16x32_bf16 v[138:141], v[122:125], v[98:101], 0
	v_mfma_f32_16x16x32_bf16 v[134:137], v[114:117], v[102:105], v[134:137]
	v_mfma_f32_16x16x32_bf16 v[138:141], v[126:129], v[102:105], v[138:141]
	v_mfma_f32_16x16x32_bf16 v[134:137], v[118:121], v[106:109], v[134:137]
	v_mfma_f32_16x16x32_bf16 v[138:141], v[130:133], v[106:109], v[138:141]
	v_fmac_f32_dpp v167, v167, v166 row_shr:1 row_mask:0xf bank_mask:0xf bound_ctrl:1
	v_fmac_f32_dpp v205, v205, v204 row_shr:1 row_mask:0xf bank_mask:0xf bound_ctrl:1
	v_fmac_f32_dpp v211, v211, v210 row_shr:1 row_mask:0xf bank_mask:0xf bound_ctrl:1
	v_fmac_f32_dpp v217, v217, v216 row_shr:1 row_mask:0xf bank_mask:0xf bound_ctrl:1
	v_mul_f32_dpp v166, v166, v166 row_shr:1 row_mask:0xf bank_mask:0xf
	v_mul_f32_dpp v204, v204, v204 row_shr:1 row_mask:0xf bank_mask:0xf
	v_mul_f32_dpp v210, v210, v210 row_shr:1 row_mask:0xf bank_mask:0xf
	v_mul_f32_dpp v216, v216, v216 row_shr:1 row_mask:0xf bank_mask:0xf
	v_fmac_f32_dpp v167, v167, v166 row_shr:2 row_mask:0xf bank_mask:0xf bound_ctrl:1
	v_fmac_f32_dpp v205, v205, v204 row_shr:2 row_mask:0xf bank_mask:0xf bound_ctrl:1
	v_fmac_f32_dpp v211, v211, v210 row_shr:2 row_mask:0xf bank_mask:0xf bound_ctrl:1
	v_fmac_f32_dpp v217, v217, v216 row_shr:2 row_mask:0xf bank_mask:0xf bound_ctrl:1
	v_mul_f32_dpp v166, v166, v166 row_shr:2 row_mask:0xf bank_mask:0xf
	v_mul_f32_dpp v204, v204, v204 row_shr:2 row_mask:0xf bank_mask:0xf
	v_mul_f32_dpp v210, v210, v210 row_shr:2 row_mask:0xf bank_mask:0xf
	v_mul_f32_dpp v216, v216, v216 row_shr:2 row_mask:0xf bank_mask:0xf
	v_fmac_f32_dpp v167, v167, v166 row_shr:4 row_mask:0xf bank_mask:0xf bound_ctrl:1
	v_fmac_f32_dpp v205, v205, v204 row_shr:4 row_mask:0xf bank_mask:0xf bound_ctrl:1
	v_fmac_f32_dpp v211, v211, v210 row_shr:4 row_mask:0xf bank_mask:0xf bound_ctrl:1
	v_fmac_f32_dpp v217, v217, v216 row_shr:4 row_mask:0xf bank_mask:0xf bound_ctrl:1
	v_mul_f32_dpp v166, v166, v166 row_shr:4 row_mask:0xf bank_mask:0xf
	v_mul_f32_dpp v204, v204, v204 row_shr:4 row_mask:0xf bank_mask:0xf
	v_mul_f32_dpp v210, v210, v210 row_shr:4 row_mask:0xf bank_mask:0xf
	v_mul_f32_dpp v216, v216, v216 row_shr:4 row_mask:0xf bank_mask:0xf
	v_fmac_f32_dpp v167, v167, v166 row_shr:8 row_mask:0xf bank_mask:0xf bound_ctrl:1
	v_fmac_f32_dpp v205, v205, v204 row_shr:8 row_mask:0xf bank_mask:0xf bound_ctrl:1
	v_fmac_f32_dpp v211, v211, v210 row_shr:8 row_mask:0xf bank_mask:0xf bound_ctrl:1
	v_fmac_f32_dpp v217, v217, v216 row_shr:8 row_mask:0xf bank_mask:0xf bound_ctrl:1
	v_mul_f32_dpp v166, v166, v166 row_shr:8 row_mask:0xf bank_mask:0xf
	v_mul_f32_dpp v204, v204, v204 row_shr:8 row_mask:0xf bank_mask:0xf
	v_mul_f32_dpp v210, v210, v210 row_shr:8 row_mask:0xf bank_mask:0xf
	v_mul_f32_dpp v216, v216, v216 row_shr:8 row_mask:0xf bank_mask:0xf
	v_fma_f32 v168, v166, v4, v167
	v_fma_f32 v206, v204, v5, v205
	v_fma_f32 v212, v210, v6, v211
	v_fma_f32 v218, v216, v7, v217
	ds_bpermute_b32 v4, v232, v168
	ds_bpermute_b32 v5, v232, v206
	ds_bpermute_b32 v6, v232, v212
	ds_bpermute_b32 v7, v232, v218
	ds_bpermute_b32 v222, v232, v166
	ds_bpermute_b32 v223, v232, v204
	ds_bpermute_b32 v224, v232, v210
	ds_bpermute_b32 v225, v232, v216
	ds_read_b128 v[110:113], v229 offset:9984
	ds_read_b128 v[122:125], v229 offset:29952
	ds_read_b128 v[114:117], v229 offset:10048
	ds_read_b128 v[126:129], v229 offset:30016
	ds_read_b128 v[118:121], v229 offset:10112
	ds_read_b128 v[130:133], v229 offset:30080
	v_fmamk_f32 v166, v134, 0xbfb8aa3b, v150
	v_fmamk_f32 v204, v135, 0xbfb8aa3b, v151
	v_fmamk_f32 v210, v136, 0xbfb8aa3b, v152
	v_fmamk_f32 v216, v137, 0xbfb8aa3b, v153
	v_fmamk_f32 v167, v138, 0xbfb8aa3b, v154
	v_fmamk_f32 v205, v139, 0xbfb8aa3b, v155
	v_fmamk_f32 v211, v140, 0xbfb8aa3b, v156
	v_fmamk_f32 v217, v141, 0xbfb8aa3b, v157
	v_exp_f32_e32 v166, v166
	v_exp_f32_e32 v204, v204
	v_exp_f32_e32 v210, v210
	v_exp_f32_e32 v216, v216
	v_exp_f32_e32 v167, v167
	v_exp_f32_e32 v205, v205
	v_exp_f32_e32 v211, v211
	v_exp_f32_e32 v217, v217
	v_add_f32_e32 v166, 1.0, v166
	v_add_f32_e32 v204, 1.0, v204
	v_add_f32_e32 v210, 1.0, v210
	v_add_f32_e32 v216, 1.0, v216
	v_add_f32_e32 v167, 1.0, v167
	v_add_f32_e32 v205, 1.0, v205
	v_add_f32_e32 v211, 1.0, v211
	v_add_f32_e32 v217, 1.0, v217
	v_rcp_f32_e32 v166, v166
	v_rcp_f32_e32 v204, v204
	v_rcp_f32_e32 v210, v210
	v_rcp_f32_e32 v216, v216
	v_rcp_f32_e32 v167, v167
	v_rcp_f32_e32 v205, v205
	v_rcp_f32_e32 v211, v211
	v_rcp_f32_e32 v217, v217
	v_mul_f32_e32 v168, v158, v166
	v_mul_f32_e32 v206, v159, v204
	v_mul_f32_e32 v212, v160, v210
	v_mul_f32_e32 v218, v161, v216
	v_mul_f32_e32 v167, v162, v167
	v_mul_f32_e32 v205, v163, v205
	v_mul_f32_e32 v211, v164, v211
	v_mul_f32_e32 v217, v165, v217
	ds_read_b128 v[150:153], v230 offset:192
	ds_read_b128 v[154:157], v230 offset:576
	ds_read_b128 v[158:161], v230 offset:960
	ds_read_b128 v[162:165], v231 offset:192
	v_exp_f32_e32 v166, v168
	v_exp_f32_e32 v204, v206
	v_exp_f32_e32 v210, v212
	v_exp_f32_e32 v216, v218
	v_fmaak_f32 v170, v168, v248, 0xbe1d955b
	v_fmaak_f32 v208, v206, v248, 0xbe1d955b
	v_fmaak_f32 v214, v212, v248, 0xbe1d955b
	v_fmaak_f32 v220, v218, v248, 0xbe1d955b
	v_fmaak_f32 v170, v168, v170, 0xbee35847
	v_fmaak_f32 v208, v206, v208, 0xbee35847
	v_fmaak_f32 v214, v212, v214, 0xbee35847
	v_fmaak_f32 v220, v218, v220, 0xbee35847
	v_min3_f32 v169, v168, v206, v212
	v_fmaak_f32 v170, v168, v170, 0xbf75fdf0
	v_fmaak_f32 v208, v206, v208, 0xbf75fdf0
	v_fmaak_f32 v214, v212, v214, 0xbf75fdf0
	v_fmaak_f32 v220, v218, v220, 0xbf75fdf0
	v_min_f32_e32 v169, v169, v218
	v_fmaak_f32 v170, v168, v170, 0xbfb17218
	v_fmaak_f32 v208, v206, v208, 0xbfb17218
	v_fmaak_f32 v214, v212, v214, 0xbfb17218
	v_fmaak_f32 v220, v218, v220, 0xbfb17218
	v_cmp_nlt_f32_e32 vcc, 0xbe38aa3b, v169
	v_mul_f32_e32 v170, v170, v168
	v_mul_f32_e32 v208, v208, v206
	v_mul_f32_e32 v214, v214, v212
	v_mul_f32_e32 v220, v220, v218
	s_cbranch_vccnz .Lscan1_far2
.Lscan1_back2:
	v_sqrt_f32_e32 v170, v170
	v_sqrt_f32_e32 v208, v208
	v_sqrt_f32_e32 v214, v214
	v_sqrt_f32_e32 v220, v220
	v_mul_f32_e32 v167, v167, v170
	v_mul_f32_e32 v205, v205, v208
	v_mul_f32_e32 v211, v211, v214
	v_mul_f32_e32 v217, v217, v220
	s_waitcnt lgkmcnt(0)
	v_mul_f32_e32 v28, v28, v222
	v_mul_f32_e32 v29, v29, v223
	v_mul_f32_e32 v30, v30, v224
	v_mul_f32_e32 v31, v31, v225
	v_mfma_f32_16x16x32_bf16 v[142:145], v[110:113], v[98:101], 0
	v_mfma_f32_16x16x32_bf16 v[146:149], v[122:125], v[98:101], 0
	v_mfma_f32_16x16x32_bf16 v[142:145], v[114:117], v[102:105], v[142:145]
	v_mfma_f32_16x16x32_bf16 v[146:149], v[126:129], v[102:105], v[146:149]
	v_mfma_f32_16x16x32_bf16 v[142:145], v[118:121], v[106:109], v[142:145]
	v_mfma_f32_16x16x32_bf16 v[146:149], v[130:133], v[106:109], v[146:149]
	v_fmac_f32_dpp v167, v167, v166 row_shr:1 row_mask:0xf bank_mask:0xf bound_ctrl:1
	v_fmac_f32_dpp v205, v205, v204 row_shr:1 row_mask:0xf bank_mask:0xf bound_ctrl:1
	v_fmac_f32_dpp v211, v211, v210 row_shr:1 row_mask:0xf bank_mask:0xf bound_ctrl:1
	v_fmac_f32_dpp v217, v217, v216 row_shr:1 row_mask:0xf bank_mask:0xf bound_ctrl:1
	v_mul_f32_dpp v166, v166, v166 row_shr:1 row_mask:0xf bank_mask:0xf
	v_mul_f32_dpp v204, v204, v204 row_shr:1 row_mask:0xf bank_mask:0xf
	v_mul_f32_dpp v210, v210, v210 row_shr:1 row_mask:0xf bank_mask:0xf
	v_mul_f32_dpp v216, v216, v216 row_shr:1 row_mask:0xf bank_mask:0xf
	v_fmac_f32_dpp v167, v167, v166 row_shr:2 row_mask:0xf bank_mask:0xf bound_ctrl:1
	v_fmac_f32_dpp v205, v205, v204 row_shr:2 row_mask:0xf bank_mask:0xf bound_ctrl:1
	v_fmac_f32_dpp v211, v211, v210 row_shr:2 row_mask:0xf bank_mask:0xf bound_ctrl:1
	v_fmac_f32_dpp v217, v217, v216 row_shr:2 row_mask:0xf bank_mask:0xf bound_ctrl:1
	v_mul_f32_dpp v166, v166, v166 row_shr:2 row_mask:0xf bank_mask:0xf
	v_mul_f32_dpp v204, v204, v204 row_shr:2 row_mask:0xf bank_mask:0xf
	v_mul_f32_dpp v210, v210, v210 row_shr:2 row_mask:0xf bank_mask:0xf
	v_mul_f32_dpp v216, v216, v216 row_shr:2 row_mask:0xf bank_mask:0xf
	v_fmac_f32_dpp v167, v167, v166 row_shr:4 row_mask:0xf bank_mask:0xf bound_ctrl:1
	v_fmac_f32_dpp v205, v205, v204 row_shr:4 row_mask:0xf bank_mask:0xf bound_ctrl:1
	v_fmac_f32_dpp v211, v211, v210 row_shr:4 row_mask:0xf bank_mask:0xf bound_ctrl:1
	v_fmac_f32_dpp v217, v217, v216 row_shr:4 row_mask:0xf bank_mask:0xf bound_ctrl:1
	v_mul_f32_dpp v166, v166, v166 row_shr:4 row_mask:0xf bank_mask:0xf
	v_mul_f32_dpp v204, v204, v204 row_shr:4 row_mask:0xf bank_mask:0xf
	v_mul_f32_dpp v210, v210, v210 row_shr:4 row_mask:0xf bank_mask:0xf
	v_mul_f32_dpp v216, v216, v216 row_shr:4 row_mask:0xf bank_mask:0xf
	v_fmac_f32_dpp v167, v167, v166 row_shr:8 row_mask:0xf bank_mask:0xf bound_ctrl:1
	v_fmac_f32_dpp v205, v205, v204 row_shr:8 row_mask:0xf bank_mask:0xf bound_ctrl:1
	v_fmac_f32_dpp v211, v211, v210 row_shr:8 row_mask:0xf bank_mask:0xf bound_ctrl:1
	v_fmac_f32_dpp v217, v217, v216 row_shr:8 row_mask:0xf bank_mask:0xf bound_ctrl:1
	v_mul_f32_dpp v166, v166, v166 row_shr:8 row_mask:0xf bank_mask:0xf
	v_mul_f32_dpp v204, v204, v204 row_shr:8 row_mask:0xf bank_mask:0xf
	v_mul_f32_dpp v210, v210, v210 row_shr:8 row_mask:0xf bank_mask:0xf
	v_mul_f32_dpp v216, v216, v216 row_shr:8 row_mask:0xf bank_mask:0xf
	v_fma_f32 v168, v166, v8, v167
	v_fma_f32 v206, v204, v9, v205
	v_fma_f32 v212, v210, v10, v211
	v_fma_f32 v218, v216, v11, v217
	ds_bpermute_b32 v8, v232, v168
	ds_bpermute_b32 v9, v232, v206
	ds_bpermute_b32 v10, v232, v212
	ds_bpermute_b32 v11, v232, v218
	ds_bpermute_b32 v222, v232, v166
	ds_bpermute_b32 v223, v232, v204
	ds_bpermute_b32 v224, v232, v210
	ds_bpermute_b32 v225, v232, v216
	ds_read_b128 v[110:113], v229 offset:13312
	ds_read_b128 v[122:125], v229 offset:33280
	ds_read_b128 v[114:117], v229 offset:13376
	ds_read_b128 v[126:129], v229 offset:33344
	ds_read_b128 v[118:121], v229 offset:13440
	ds_read_b128 v[130:133], v229 offset:33408
	v_fmamk_f32 v166, v142, 0xbfb8aa3b, v150
	v_fmamk_f32 v204, v143, 0xbfb8aa3b, v151
	v_fmamk_f32 v210, v144, 0xbfb8aa3b, v152
	v_fmamk_f32 v216, v145, 0xbfb8aa3b, v153
	v_fmamk_f32 v167, v146, 0xbfb8aa3b, v154
	v_fmamk_f32 v205, v147, 0xbfb8aa3b, v155
	v_fmamk_f32 v211, v148, 0xbfb8aa3b, v156
	v_fmamk_f32 v217, v149, 0xbfb8aa3b, v157
	v_exp_f32_e32 v166, v166
	v_exp_f32_e32 v204, v204
	v_exp_f32_e32 v210, v210
	v_exp_f32_e32 v216, v216
	v_exp_f32_e32 v167, v167
	v_exp_f32_e32 v205, v205
	v_exp_f32_e32 v211, v211
	v_exp_f32_e32 v217, v217
	v_add_f32_e32 v166, 1.0, v166
	v_add_f32_e32 v204, 1.0, v204
	v_add_f32_e32 v210, 1.0, v210
	v_add_f32_e32 v216, 1.0, v216
	v_add_f32_e32 v167, 1.0, v167
	v_add_f32_e32 v205, 1.0, v205
	v_add_f32_e32 v211, 1.0, v211
	v_add_f32_e32 v217, 1.0, v217
	v_rcp_f32_e32 v166, v166
	v_rcp_f32_e32 v204, v204
	v_rcp_f32_e32 v210, v210
	v_rcp_f32_e32 v216, v216
	v_rcp_f32_e32 v167, v167
	v_rcp_f32_e32 v205, v205
	v_rcp_f32_e32 v211, v211
	v_rcp_f32_e32 v217, v217
	v_mul_f32_e32 v168, v158, v166
	v_mul_f32_e32 v206, v159, v204
	v_mul_f32_e32 v212, v160, v210
	v_mul_f32_e32 v218, v161, v216
	v_mul_f32_e32 v167, v162, v167
	v_mul_f32_e32 v205, v163, v205
	v_mul_f32_e32 v211, v164, v211
	v_mul_f32_e32 v217, v165, v217
	ds_read_b128 v[150:153], v230 offset:256
	ds_read_b128 v[154:157], v230 offset:640
	ds_read_b128 v[158:161], v230 offset:1024
	ds_read_b128 v[162:165], v231 offset:256
	v_exp_f32_e32 v166, v168
	v_exp_f32_e32 v204, v206
	v_exp_f32_e32 v210, v212
	v_exp_f32_e32 v216, v218
	v_fmaak_f32 v170, v168, v248, 0xbe1d955b
	v_fmaak_f32 v208, v206, v248, 0xbe1d955b
	v_fmaak_f32 v214, v212, v248, 0xbe1d955b
	v_fmaak_f32 v220, v218, v248, 0xbe1d955b
	v_fmaak_f32 v170, v168, v170, 0xbee35847
	v_fmaak_f32 v208, v206, v208, 0xbee35847
	v_fmaak_f32 v214, v212, v214, 0xbee35847
	v_fmaak_f32 v220, v218, v220, 0xbee35847
	v_min3_f32 v169, v168, v206, v212
	v_fmaak_f32 v170, v168, v170, 0xbf75fdf0
	v_fmaak_f32 v208, v206, v208, 0xbf75fdf0
	v_fmaak_f32 v214, v212, v214, 0xbf75fdf0
	v_fmaak_f32 v220, v218, v220, 0xbf75fdf0
	v_min_f32_e32 v169, v169, v218
	v_fmaak_f32 v170, v168, v170, 0xbfb17218
	v_fmaak_f32 v208, v206, v208, 0xbfb17218
	v_fmaak_f32 v214, v212, v214, 0xbfb17218
	v_fmaak_f32 v220, v218, v220, 0xbfb17218
	v_cmp_nlt_f32_e32 vcc, 0xbe38aa3b, v169
	v_mul_f32_e32 v170, v170, v168
	v_mul_f32_e32 v208, v208, v206
	v_mul_f32_e32 v214, v214, v212
	v_mul_f32_e32 v220, v220, v218
	s_cbranch_vccnz .Lscan1_far3
.Lscan1_back3:
	v_sqrt_f32_e32 v170, v170
	v_sqrt_f32_e32 v208, v208
	v_sqrt_f32_e32 v214, v214
	v_sqrt_f32_e32 v220, v220
	v_mul_f32_e32 v167, v167, v170
	v_mul_f32_e32 v205, v205, v208
	v_mul_f32_e32 v211, v211, v214
	v_mul_f32_e32 v217, v217, v220
	s_waitcnt lgkmcnt(0)
	v_mul_f32_e32 v32, v32, v222
	v_mul_f32_e32 v33, v33, v223
	v_mul_f32_e32 v34, v34, v224
	v_mul_f32_e32 v35, v35, v225
	v_mfma_f32_16x16x32_bf16 v[134:137], v[110:113], v[98:101], 0
	v_mfma_f32_16x16x32_bf16 v[138:141], v[122:125], v[98:101], 0
	v_mfma_f32_16x16x32_bf16 v[134:137], v[114:117], v[102:105], v[134:137]
	v_mfma_f32_16x16x32_bf16 v[138:141], v[126:129], v[102:105], v[138:141]
	v_mfma_f32_16x16x32_bf16 v[134:137], v[118:121], v[106:109], v[134:137]
	v_mfma_f32_16x16x32_bf16 v[138:141], v[130:133], v[106:109], v[138:141]
	v_fmac_f32_dpp v167, v167, v166 row_shr:1 row_mask:0xf bank_mask:0xf bound_ctrl:1
	v_fmac_f32_dpp v205, v205, v204 row_shr:1 row_mask:0xf bank_mask:0xf bound_ctrl:1
	v_fmac_f32_dpp v211, v211, v210 row_shr:1 row_mask:0xf bank_mask:0xf bound_ctrl:1
	v_fmac_f32_dpp v217, v217, v216 row_shr:1 row_mask:0xf bank_mask:0xf bound_ctrl:1
	v_mul_f32_dpp v166, v166, v166 row_shr:1 row_mask:0xf bank_mask:0xf
	v_mul_f32_dpp v204, v204, v204 row_shr:1 row_mask:0xf bank_mask:0xf
	v_mul_f32_dpp v210, v210, v210 row_shr:1 row_mask:0xf bank_mask:0xf
	v_mul_f32_dpp v216, v216, v216 row_shr:1 row_mask:0xf bank_mask:0xf
	v_fmac_f32_dpp v167, v167, v166 row_shr:2 row_mask:0xf bank_mask:0xf bound_ctrl:1
	v_fmac_f32_dpp v205, v205, v204 row_shr:2 row_mask:0xf bank_mask:0xf bound_ctrl:1
	v_fmac_f32_dpp v211, v211, v210 row_shr:2 row_mask:0xf bank_mask:0xf bound_ctrl:1
	v_fmac_f32_dpp v217, v217, v216 row_shr:2 row_mask:0xf bank_mask:0xf bound_ctrl:1
	v_mul_f32_dpp v166, v166, v166 row_shr:2 row_mask:0xf bank_mask:0xf
	v_mul_f32_dpp v204, v204, v204 row_shr:2 row_mask:0xf bank_mask:0xf
	v_mul_f32_dpp v210, v210, v210 row_shr:2 row_mask:0xf bank_mask:0xf
	v_mul_f32_dpp v216, v216, v216 row_shr:2 row_mask:0xf bank_mask:0xf
	v_fmac_f32_dpp v167, v167, v166 row_shr:4 row_mask:0xf bank_mask:0xf bound_ctrl:1
	v_fmac_f32_dpp v205, v205, v204 row_shr:4 row_mask:0xf bank_mask:0xf bound_ctrl:1
	v_fmac_f32_dpp v211, v211, v210 row_shr:4 row_mask:0xf bank_mask:0xf bound_ctrl:1
	v_fmac_f32_dpp v217, v217, v216 row_shr:4 row_mask:0xf bank_mask:0xf bound_ctrl:1
	v_mul_f32_dpp v166, v166, v166 row_shr:4 row_mask:0xf bank_mask:0xf
	v_mul_f32_dpp v204, v204, v204 row_shr:4 row_mask:0xf bank_mask:0xf
	v_mul_f32_dpp v210, v210, v210 row_shr:4 row_mask:0xf bank_mask:0xf
	v_mul_f32_dpp v216, v216, v216 row_shr:4 row_mask:0xf bank_mask:0xf
	v_fmac_f32_dpp v167, v167, v166 row_shr:8 row_mask:0xf bank_mask:0xf bound_ctrl:1
	v_fmac_f32_dpp v205, v205, v204 row_shr:8 row_mask:0xf bank_mask:0xf bound_ctrl:1
	v_fmac_f32_dpp v211, v211, v210 row_shr:8 row_mask:0xf bank_mask:0xf bound_ctrl:1
	v_fmac_f32_dpp v217, v217, v216 row_shr:8 row_mask:0xf bank_mask:0xf bound_ctrl:1
	v_mul_f32_dpp v166, v166, v166 row_shr:8 row_mask:0xf bank_mask:0xf
	v_mul_f32_dpp v204, v204, v204 row_shr:8 row_mask:0xf bank_mask:0xf
	v_mul_f32_dpp v210, v210, v210 row_shr:8 row_mask:0xf bank_mask:0xf
	v_mul_f32_dpp v216, v216, v216 row_shr:8 row_mask:0xf bank_mask:0xf
	v_fma_f32 v168, v166, v12, v167
	v_fma_f32 v206, v204, v13, v205
	v_fma_f32 v212, v210, v14, v211
	v_fma_f32 v218, v216, v15, v217
	ds_bpermute_b32 v12, v232, v168
	ds_bpermute_b32 v13, v232, v206
	ds_bpermute_b32 v14, v232, v212
	ds_bpermute_b32 v15, v232, v218
	ds_bpermute_b32 v222, v232, v166
	ds_bpermute_b32 v223, v232, v204
	ds_bpermute_b32 v224, v232, v210
	ds_bpermute_b32 v225, v232, v216
	ds_read_b128 v[110:113], v229 offset:16640
	ds_read_b128 v[122:125], v229 offset:36608
	ds_read_b128 v[114:117], v229 offset:16704
	ds_read_b128 v[126:129], v229 offset:36672
	ds_read_b128 v[118:121], v229 offset:16768
	ds_read_b128 v[130:133], v229 offset:36736
	v_fmamk_f32 v166, v134, 0xbfb8aa3b, v150
	v_fmamk_f32 v204, v135, 0xbfb8aa3b, v151
	v_fmamk_f32 v210, v136, 0xbfb8aa3b, v152
	v_fmamk_f32 v216, v137, 0xbfb8aa3b, v153
	v_fmamk_f32 v167, v138, 0xbfb8aa3b, v154
	v_fmamk_f32 v205, v139, 0xbfb8aa3b, v155
	v_fmamk_f32 v211, v140, 0xbfb8aa3b, v156
	v_fmamk_f32 v217, v141, 0xbfb8aa3b, v157
	v_exp_f32_e32 v166, v166
	v_exp_f32_e32 v204, v204
	v_exp_f32_e32 v210, v210
	v_exp_f32_e32 v216, v216
	v_exp_f32_e32 v167, v167
	v_exp_f32_e32 v205, v205
	v_exp_f32_e32 v211, v211
	v_exp_f32_e32 v217, v217
	v_add_f32_e32 v166, 1.0, v166
	v_add_f32_e32 v204, 1.0, v204
	v_add_f32_e32 v210, 1.0, v210
	v_add_f32_e32 v216, 1.0, v216
	v_add_f32_e32 v167, 1.0, v167
	v_add_f32_e32 v205, 1.0, v205
	v_add_f32_e32 v211, 1.0, v211
	v_add_f32_e32 v217, 1.0, v217
	v_rcp_f32_e32 v166, v166
	v_rcp_f32_e32 v204, v204
	v_rcp_f32_e32 v210, v210
	v_rcp_f32_e32 v216, v216
	v_rcp_f32_e32 v167, v167
	v_rcp_f32_e32 v205, v205
	v_rcp_f32_e32 v211, v211
	v_rcp_f32_e32 v217, v217
	v_mul_f32_e32 v168, v158, v166
	v_mul_f32_e32 v206, v159, v204
	v_mul_f32_e32 v212, v160, v210
	v_mul_f32_e32 v218, v161, v216
	v_mul_f32_e32 v167, v162, v167
	v_mul_f32_e32 v205, v163, v205
	v_mul_f32_e32 v211, v164, v211
	v_mul_f32_e32 v217, v165, v217
	ds_read_b128 v[150:153], v230 offset:320
	ds_read_b128 v[154:157], v230 offset:704
	ds_read_b128 v[158:161], v230 offset:1088
	ds_read_b128 v[162:165], v231 offset:320
	v_exp_f32_e32 v166, v168
	v_exp_f32_e32 v204, v206
	v_exp_f32_e32 v210, v212
	v_exp_f32_e32 v216, v218
	v_fmaak_f32 v170, v168, v248, 0xbe1d955b
	v_fmaak_f32 v208, v206, v248, 0xbe1d955b
	v_fmaak_f32 v214, v212, v248, 0xbe1d955b
	v_fmaak_f32 v220, v218, v248, 0xbe1d955b
	v_fmaak_f32 v170, v168, v170, 0xbee35847
	v_fmaak_f32 v208, v206, v208, 0xbee35847
	v_fmaak_f32 v214, v212, v214, 0xbee35847
	v_fmaak_f32 v220, v218, v220, 0xbee35847
	v_min3_f32 v169, v168, v206, v212
	v_fmaak_f32 v170, v168, v170, 0xbf75fdf0
	v_fmaak_f32 v208, v206, v208, 0xbf75fdf0
	v_fmaak_f32 v214, v212, v214, 0xbf75fdf0
	v_fmaak_f32 v220, v218, v220, 0xbf75fdf0
	v_min_f32_e32 v169, v169, v218
	v_fmaak_f32 v170, v168, v170, 0xbfb17218
	v_fmaak_f32 v208, v206, v208, 0xbfb17218
	v_fmaak_f32 v214, v212, v214, 0xbfb17218
	v_fmaak_f32 v220, v218, v220, 0xbfb17218
	v_cmp_nlt_f32_e32 vcc, 0xbe38aa3b, v169
	v_mul_f32_e32 v170, v170, v168
	v_mul_f32_e32 v208, v208, v206
	v_mul_f32_e32 v214, v214, v212
	v_mul_f32_e32 v220, v220, v218
	s_cbranch_vccnz .Lscan1_far4
.Lscan1_back4:
	v_sqrt_f32_e32 v170, v170
	v_sqrt_f32_e32 v208, v208
	v_sqrt_f32_e32 v214, v214
	v_sqrt_f32_e32 v220, v220
	v_mul_f32_e32 v167, v167, v170
	v_mul_f32_e32 v205, v205, v208
	v_mul_f32_e32 v211, v211, v214
	v_mul_f32_e32 v217, v217, v220
	s_waitcnt lgkmcnt(0)
	v_mul_f32_e32 v36, v36, v222
	v_mul_f32_e32 v37, v37, v223
	v_mul_f32_e32 v38, v38, v224
	v_mul_f32_e32 v39, v39, v225
	v_mfma_f32_16x16x32_bf16 v[142:145], v[110:113], v[98:101], 0
	v_mfma_f32_16x16x32_bf16 v[146:149], v[122:125], v[98:101], 0
	v_mfma_f32_16x16x32_bf16 v[142:145], v[114:117], v[102:105], v[142:145]
	v_mfma_f32_16x16x32_bf16 v[146:149], v[126:129], v[102:105], v[146:149]
	v_mfma_f32_16x16x32_bf16 v[142:145], v[118:121], v[106:109], v[142:145]
	v_mfma_f32_16x16x32_bf16 v[146:149], v[130:133], v[106:109], v[146:149]
	v_fmac_f32_dpp v167, v167, v166 row_shr:1 row_mask:0xf bank_mask:0xf bound_ctrl:1
	v_fmac_f32_dpp v205, v205, v204 row_shr:1 row_mask:0xf bank_mask:0xf bound_ctrl:1
	v_fmac_f32_dpp v211, v211, v210 row_shr:1 row_mask:0xf bank_mask:0xf bound_ctrl:1
	v_fmac_f32_dpp v217, v217, v216 row_shr:1 row_mask:0xf bank_mask:0xf bound_ctrl:1
	v_mul_f32_dpp v166, v166, v166 row_shr:1 row_mask:0xf bank_mask:0xf
	v_mul_f32_dpp v204, v204, v204 row_shr:1 row_mask:0xf bank_mask:0xf
	v_mul_f32_dpp v210, v210, v210 row_shr:1 row_mask:0xf bank_mask:0xf
	v_mul_f32_dpp v216, v216, v216 row_shr:1 row_mask:0xf bank_mask:0xf
	v_fmac_f32_dpp v167, v167, v166 row_shr:2 row_mask:0xf bank_mask:0xf bound_ctrl:1
	v_fmac_f32_dpp v205, v205, v204 row_shr:2 row_mask:0xf bank_mask:0xf bound_ctrl:1
	v_fmac_f32_dpp v211, v211, v210 row_shr:2 row_mask:0xf bank_mask:0xf bound_ctrl:1
	v_fmac_f32_dpp v217, v217, v216 row_shr:2 row_mask:0xf bank_mask:0xf bound_ctrl:1
	v_mul_f32_dpp v166, v166, v166 row_shr:2 row_mask:0xf bank_mask:0xf
	v_mul_f32_dpp v204, v204, v204 row_shr:2 row_mask:0xf bank_mask:0xf
	v_mul_f32_dpp v210, v210, v210 row_shr:2 row_mask:0xf bank_mask:0xf
	v_mul_f32_dpp v216, v216, v216 row_shr:2 row_mask:0xf bank_mask:0xf
	v_fmac_f32_dpp v167, v167, v166 row_shr:4 row_mask:0xf bank_mask:0xf bound_ctrl:1
	v_fmac_f32_dpp v205, v205, v204 row_shr:4 row_mask:0xf bank_mask:0xf bound_ctrl:1
	v_fmac_f32_dpp v211, v211, v210 row_shr:4 row_mask:0xf bank_mask:0xf bound_ctrl:1
	v_fmac_f32_dpp v217, v217, v216 row_shr:4 row_mask:0xf bank_mask:0xf bound_ctrl:1
	v_mul_f32_dpp v166, v166, v166 row_shr:4 row_mask:0xf bank_mask:0xf
	v_mul_f32_dpp v204, v204, v204 row_shr:4 row_mask:0xf bank_mask:0xf
	v_mul_f32_dpp v210, v210, v210 row_shr:4 row_mask:0xf bank_mask:0xf
	v_mul_f32_dpp v216, v216, v216 row_shr:4 row_mask:0xf bank_mask:0xf
	v_fmac_f32_dpp v167, v167, v166 row_shr:8 row_mask:0xf bank_mask:0xf bound_ctrl:1
	v_fmac_f32_dpp v205, v205, v204 row_shr:8 row_mask:0xf bank_mask:0xf bound_ctrl:1
	v_fmac_f32_dpp v211, v211, v210 row_shr:8 row_mask:0xf bank_mask:0xf bound_ctrl:1
	v_fmac_f32_dpp v217, v217, v216 row_shr:8 row_mask:0xf bank_mask:0xf bound_ctrl:1
	v_mul_f32_dpp v166, v166, v166 row_shr:8 row_mask:0xf bank_mask:0xf
	v_mul_f32_dpp v204, v204, v204 row_shr:8 row_mask:0xf bank_mask:0xf
	v_mul_f32_dpp v210, v210, v210 row_shr:8 row_mask:0xf bank_mask:0xf
	v_mul_f32_dpp v216, v216, v216 row_shr:8 row_mask:0xf bank_mask:0xf
	v_fma_f32 v168, v166, v16, v167
	v_fma_f32 v206, v204, v17, v205
	v_fma_f32 v212, v210, v18, v211
	v_fma_f32 v218, v216, v19, v217
	ds_bpermute_b32 v16, v232, v168
	ds_bpermute_b32 v17, v232, v206
	ds_bpermute_b32 v18, v232, v212
	ds_bpermute_b32 v19, v232, v218
	ds_bpermute_b32 v222, v232, v166
	ds_bpermute_b32 v223, v232, v204
	ds_bpermute_b32 v224, v232, v210
	ds_bpermute_b32 v225, v232, v216
	v_fmamk_f32 v166, v142, 0xbfb8aa3b, v150
	v_fmamk_f32 v204, v143, 0xbfb8aa3b, v151
	v_fmamk_f32 v210, v144, 0xbfb8aa3b, v152
	v_fmamk_f32 v216, v145, 0xbfb8aa3b, v153
	v_fmamk_f32 v167, v146, 0xbfb8aa3b, v154
	v_fmamk_f32 v205, v147, 0xbfb8aa3b, v155
	v_fmamk_f32 v211, v148, 0xbfb8aa3b, v156
	v_fmamk_f32 v217, v149, 0xbfb8aa3b, v157
	v_exp_f32_e32 v166, v166
	v_exp_f32_e32 v204, v204
	v_exp_f32_e32 v210, v210
	v_exp_f32_e32 v216, v216
	v_exp_f32_e32 v167, v167
	v_exp_f32_e32 v205, v205
	v_exp_f32_e32 v211, v211
	v_exp_f32_e32 v217, v217
	v_add_f32_e32 v166, 1.0, v166
	v_add_f32_e32 v204, 1.0, v204
	v_add_f32_e32 v210, 1.0, v210
	v_add_f32_e32 v216, 1.0, v216
	v_add_f32_e32 v167, 1.0, v167
	v_add_f32_e32 v205, 1.0, v205
	v_add_f32_e32 v211, 1.0, v211
	v_add_f32_e32 v217, 1.0, v217
	v_rcp_f32_e32 v166, v166
	v_rcp_f32_e32 v204, v204
	v_rcp_f32_e32 v210, v210
	v_rcp_f32_e32 v216, v216
	v_rcp_f32_e32 v167, v167
	v_rcp_f32_e32 v205, v205
	v_rcp_f32_e32 v211, v211
	v_rcp_f32_e32 v217, v217
	v_mul_f32_e32 v168, v158, v166
	v_mul_f32_e32 v206, v159, v204
	v_mul_f32_e32 v212, v160, v210
	v_mul_f32_e32 v218, v161, v216
	v_mul_f32_e32 v167, v162, v167
	v_mul_f32_e32 v205, v163, v205
	v_mul_f32_e32 v211, v164, v211
	v_mul_f32_e32 v217, v165, v217
	v_exp_f32_e32 v166, v168
	v_exp_f32_e32 v204, v206
	v_exp_f32_e32 v210, v212
	v_exp_f32_e32 v216, v218
	v_fmaak_f32 v170, v168, v248, 0xbe1d955b
	v_fmaak_f32 v208, v206, v248, 0xbe1d955b
	v_fmaak_f32 v214, v212, v248, 0xbe1d955b
	v_fmaak_f32 v220, v218, v248, 0xbe1d955b
	v_fmaak_f32 v170, v168, v170, 0xbee35847
	v_fmaak_f32 v208, v206, v208, 0xbee35847
	v_fmaak_f32 v214, v212, v214, 0xbee35847
	v_fmaak_f32 v220, v218, v220, 0xbee35847
	v_min3_f32 v169, v168, v206, v212
	v_fmaak_f32 v170, v168, v170, 0xbf75fdf0
	v_fmaak_f32 v208, v206, v208, 0xbf75fdf0
	v_fmaak_f32 v214, v212, v214, 0xbf75fdf0
	v_fmaak_f32 v220, v218, v220, 0xbf75fdf0
	v_min_f32_e32 v169, v169, v218
	v_fmaak_f32 v170, v168, v170, 0xbfb17218
	v_fmaak_f32 v208, v206, v208, 0xbfb17218
	v_fmaak_f32 v214, v212, v214, 0xbfb17218
	v_fmaak_f32 v220, v218, v220, 0xbfb17218
	v_cmp_nlt_f32_e32 vcc, 0xbe38aa3b, v169
	v_mul_f32_e32 v170, v170, v168
	v_mul_f32_e32 v208, v208, v206
	v_mul_f32_e32 v214, v214, v212
	v_mul_f32_e32 v220, v220, v218
	s_cbranch_vccnz .Lscan1_far5

.Lscan2_sub:
	global_load_dwordx2 v[24:25], v235, s[6:7] offset:0
	global_load_dwordx2 v[26:27], v235, s[6:7] offset:32
	global_load_dwordx2 v[28:29], v235, s[6:7] offset:64
	global_load_dwordx2 v[30:31], v235, s[6:7] offset:96
	global_load_dwordx2 v[32:33], v235, s[6:7] offset:128
	global_load_dwordx2 v[34:35], v235, s[6:7] offset:160
	s_mov_b64 s[62:63], s[44:45]
	global_load_dword v82, v233, s[62:63]
	s_add_u32 s62, s62, 0x1800
	s_addc_u32 s63, s63, 0
	global_load_dword v83, v233, s[62:63]
	s_add_u32 s62, s62, 0x1800
	s_addc_u32 s63, s63, 0
	global_load_dword v84, v233, s[62:63]
	s_add_u32 s62, s62, 0x1800
	s_addc_u32 s63, s63, 0
	global_load_dword v85, v233, s[62:63]
	s_add_u32 s62, s62, 0x1800
	s_addc_u32 s63, s63, 0
	global_load_dword v86, v233, s[62:63]
	s_add_u32 s62, s62, 0x1800
	s_addc_u32 s63, s63, 0
	global_load_dword v87, v233, s[62:63]
	s_add_u32 s62, s62, 0x1800
	s_addc_u32 s63, s63, 0
	global_load_dword v88, v233, s[62:63]
	s_add_u32 s62, s62, 0x1800
	s_addc_u32 s63, s63, 0
	global_load_dword v89, v233, s[62:63]
	s_add_u32 s62, s62, 0x1800
	s_addc_u32 s63, s63, 0
	global_load_dword v90, v233, s[62:63]
	s_add_u32 s62, s62, 0x1800
	s_addc_u32 s63, s63, 0
	global_load_dword v91, v233, s[62:63]
	s_add_u32 s62, s62, 0x1800
	s_addc_u32 s63, s63, 0
	global_load_dword v92, v233, s[62:63]
	s_add_u32 s62, s62, 0x1800
	s_addc_u32 s63, s63, 0
	global_load_dword v93, v233, s[62:63]
	s_add_u32 s62, s62, 0x1800
	s_addc_u32 s63, s63, 0
	global_load_dword v94, v233, s[62:63]
	s_add_u32 s62, s62, 0x1800
	s_addc_u32 s63, s63, 0
	global_load_dword v95, v233, s[62:63]
	s_add_u32 s62, s62, 0x1800
	s_addc_u32 s63, s63, 0
	global_load_dword v96, v233, s[62:63]
	s_add_u32 s62, s62, 0x1800
	s_addc_u32 s63, s63, 0
	global_load_dword v97, v233, s[62:63]
	s_add_u32 s62, s62, 0x1800
	s_addc_u32 s63, s63, 0
	s_mov_b64 s[44:45], s[62:63]
	ds_read_b128 v[110:113], v229 offset:0
	ds_read_b128 v[122:125], v229 offset:19968
	ds_read_b128 v[114:117], v229 offset:64
	ds_read_b128 v[126:129], v229 offset:20032
	ds_read_b128 v[118:121], v229 offset:128
	ds_read_b128 v[130:133], v229 offset:20096
	ds_read_b128 v[150:153], v230
	ds_read_b128 v[154:157], v230 offset:384
	ds_read_b128 v[158:161], v230 offset:768
	s_mov_b32 s62, -1
	s_mov_b32 s63, 0xffff
	s_mov_b64 exec, s[62:63]
	v_lshlrev_b32_e32 v64, 16, v66
	v_and_b32_e32 v65, 0xffff0000, v66
	v_fma_f32 v242, v58, v48, v56
	v_fma_f32 v243, v59, v49, v57
	v_lshlrev_b32_e32 v58, 16, v67
	v_and_b32_e32 v59, 0xffff0000, v67
	v_fma_f32 v244, v60, v48, v56
	v_fma_f32 v245, v61, v49, v57
	v_fma_f32 v242, v60, v50, v242
	v_fma_f32 v243, v61, v51, v243
	v_fma_f32 v244, v62, v50, v244
	v_fma_f32 v245, v63, v51, v245
	v_fma_f32 v242, v62, v52, v242
	v_fma_f32 v243, v63, v53, v243
	v_fma_f32 v244, v64, v52, v244
	v_fma_f32 v245, v65, v53, v245
	v_fma_f32 v242, v64, v54, v242
	v_fma_f32 v243, v65, v55, v243
	v_fma_f32 v244, v58, v54, v244
	v_fma_f32 v245, v59, v55, v245
	ds_write_b64 v226, v[242:243] offset:0
	v_cvt_pk_bf16_f32 v246, v242, v243
	ds_write_b64 v226, v[244:245] offset:400
	v_cvt_pk_bf16_f32 v247, v244, v245
	ds_write_b32 v227, v246 offset:0
	ds_write_b32 v227, v247 offset:208
	v_lshlrev_b32_e32 v60, 16, v68
	v_and_b32_e32 v61, 0xffff0000, v68
	v_fma_f32 v242, v62, v48, v56
	v_fma_f32 v243, v63, v49, v57
	v_lshlrev_b32_e32 v62, 16, v69
	v_and_b32_e32 v63, 0xffff0000, v69
	v_fma_f32 v244, v64, v48, v56
	v_fma_f32 v245, v65, v49, v57
	v_fma_f32 v242, v64, v50, v242
	v_fma_f32 v243, v65, v51, v243
	v_fma_f32 v244, v58, v50, v244
	v_fma_f32 v245, v59, v51, v245
	v_fma_f32 v242, v58, v52, v242
	v_fma_f32 v243, v59, v53, v243
	v_fma_f32 v244, v60, v52, v244
	v_fma_f32 v245, v61, v53, v245
	v_fma_f32 v242, v60, v54, v242
	v_fma_f32 v243, v61, v55, v243
	v_fma_f32 v244, v62, v54, v244
	v_fma_f32 v245, v63, v55, v245
	ds_write_b64 v226, v[242:243] offset:800
	v_cvt_pk_bf16_f32 v246, v242, v243
	ds_write_b64 v226, v[244:245] offset:1200
	v_cvt_pk_bf16_f32 v247, v244, v245
	ds_write_b32 v227, v246 offset:416
	ds_write_b32 v227, v247 offset:624
	v_lshlrev_b32_e32 v64, 16, v70
	v_and_b32_e32 v65, 0xffff0000, v70
	v_fma_f32 v242, v58, v48, v56
	v_fma_f32 v243, v59, v49, v57
	v_lshlrev_b32_e32 v58, 16, v71
	v_and_b32_e32 v59, 0xffff0000, v71
	v_fma_f32 v244, v60, v48, v56
	v_fma_f32 v245, v61, v49, v57
	v_fma_f32 v242, v60, v50, v242
	v_fma_f32 v243, v61, v51, v243
	v_fma_f32 v244, v62, v50, v244
	v_fma_f32 v245, v63, v51, v245
	v_fma_f32 v242, v62, v52, v242
	v_fma_f32 v243, v63, v53, v243
	v_fma_f32 v244, v64, v52, v244
	v_fma_f32 v245, v65, v53, v245
	v_fma_f32 v242, v64, v54, v242
	v_fma_f32 v243, v65, v55, v243
	v_fma_f32 v244, v58, v54, v244
	v_fma_f32 v245, v59, v55, v245
	ds_write_b64 v226, v[242:243] offset:1600
	v_cvt_pk_bf16_f32 v246, v242, v243
	ds_write_b64 v226, v[244:245] offset:2000
	v_cvt_pk_bf16_f32 v247, v244, v245
	ds_write_b32 v227, v246 offset:832
	ds_write_b32 v227, v247 offset:1040
	v_lshlrev_b32_e32 v60, 16, v72
	v_and_b32_e32 v61, 0xffff0000, v72
	v_fma_f32 v242, v62, v48, v56
	v_fma_f32 v243, v63, v49, v57
	v_lshlrev_b32_e32 v62, 16, v73
	v_and_b32_e32 v63, 0xffff0000, v73
	v_fma_f32 v244, v64, v48, v56
	v_fma_f32 v245, v65, v49, v57
	v_fma_f32 v242, v64, v50, v242
	v_fma_f32 v243, v65, v51, v243
	v_fma_f32 v244, v58, v50, v244
	v_fma_f32 v245, v59, v51, v245
	v_fma_f32 v242, v58, v52, v242
	v_fma_f32 v243, v59, v53, v243
	v_fma_f32 v244, v60, v52, v244
	v_fma_f32 v245, v61, v53, v245
	v_fma_f32 v242, v60, v54, v242
	v_fma_f32 v243, v61, v55, v243
	v_fma_f32 v244, v62, v54, v244
	v_fma_f32 v245, v63, v55, v245
	ds_write_b64 v226, v[242:243] offset:2400
	v_cvt_pk_bf16_f32 v246, v242, v243
	ds_write_b64 v226, v[244:245] offset:2800
	v_cvt_pk_bf16_f32 v247, v244, v245
	ds_write_b32 v227, v246 offset:1248
	ds_write_b32 v227, v247 offset:1456
	v_lshlrev_b32_e32 v64, 16, v74
	v_and_b32_e32 v65, 0xffff0000, v74
	v_fma_f32 v242, v58, v48, v56
	v_fma_f32 v243, v59, v49, v57
	v_lshlrev_b32_e32 v58, 16, v75
	v_and_b32_e32 v59, 0xffff0000, v75
	v_fma_f32 v244, v60, v48, v56
	v_fma_f32 v245, v61, v49, v57
	v_fma_f32 v242, v60, v50, v242
	v_fma_f32 v243, v61, v51, v243
	v_fma_f32 v244, v62, v50, v244
	v_fma_f32 v245, v63, v51, v245
	v_fma_f32 v242, v62, v52, v242
	v_fma_f32 v243, v63, v53, v243
	v_fma_f32 v244, v64, v52, v244
	v_fma_f32 v245, v65, v53, v245
	v_fma_f32 v242, v64, v54, v242
	v_fma_f32 v243, v65, v55, v243
	v_fma_f32 v244, v58, v54, v244
	v_fma_f32 v245, v59, v55, v245
	ds_write_b64 v226, v[242:243] offset:3200
	v_cvt_pk_bf16_f32 v246, v242, v243
	ds_write_b64 v226, v[244:245] offset:3600
	v_cvt_pk_bf16_f32 v247, v244, v245
	ds_write_b32 v227, v246 offset:1664
	ds_write_b32 v227, v247 offset:1872
	v_lshlrev_b32_e32 v60, 16, v76
	v_and_b32_e32 v61, 0xffff0000, v76
	v_fma_f32 v242, v62, v48, v56
	v_fma_f32 v243, v63, v49, v57
	v_lshlrev_b32_e32 v62, 16, v77
	v_and_b32_e32 v63, 0xffff0000, v77
	v_fma_f32 v244, v64, v48, v56
	v_fma_f32 v245, v65, v49, v57
	v_fma_f32 v242, v64, v50, v242
	v_fma_f32 v243, v65, v51, v243
	v_fma_f32 v244, v58, v50, v244
	v_fma_f32 v245, v59, v51, v245
	v_fma_f32 v242, v58, v52, v242
	v_fma_f32 v243, v59, v53, v243
	v_fma_f32 v244, v60, v52, v244
	v_fma_f32 v245, v61, v53, v245
	v_fma_f32 v242, v60, v54, v242
	v_fma_f32 v243, v61, v55, v243
	v_fma_f32 v244, v62, v54, v244
	v_fma_f32 v245, v63, v55, v245
	ds_write_b64 v226, v[242:243] offset:4000
	v_cvt_pk_bf16_f32 v246, v242, v243
	ds_write_b64 v226, v[244:245] offset:4400
	v_cvt_pk_bf16_f32 v247, v244, v245
	ds_write_b32 v227, v246 offset:2080
	ds_write_b32 v227, v247 offset:2288
	v_lshlrev_b32_e32 v64, 16, v78
	v_and_b32_e32 v65, 0xffff0000, v78
	v_fma_f32 v242, v58, v48, v56
	v_fma_f32 v243, v59, v49, v57
	v_lshlrev_b32_e32 v58, 16, v79
	v_and_b32_e32 v59, 0xffff0000, v79
	v_fma_f32 v244, v60, v48, v56
	v_fma_f32 v245, v61, v49, v57
	v_fma_f32 v242, v60, v50, v242
	v_fma_f32 v243, v61, v51, v243
	v_fma_f32 v244, v62, v50, v244
	v_fma_f32 v245, v63, v51, v245
	v_fma_f32 v242, v62, v52, v242
	v_fma_f32 v243, v63, v53, v243
	v_fma_f32 v244, v64, v52, v244
	v_fma_f32 v245, v65, v53, v245
	v_fma_f32 v242, v64, v54, v242
	v_fma_f32 v243, v65, v55, v243
	v_fma_f32 v244, v58, v54, v244
	v_fma_f32 v245, v59, v55, v245
	ds_write_b64 v226, v[242:243] offset:4800
	v_cvt_pk_bf16_f32 v246, v242, v243
	ds_write_b64 v226, v[244:245] offset:5200
	v_cvt_pk_bf16_f32 v247, v244, v245
	ds_write_b32 v227, v246 offset:2496
	ds_write_b32 v227, v247 offset:2704
	v_lshlrev_b32_e32 v60, 16, v80
	v_and_b32_e32 v61, 0xffff0000, v80
	v_fma_f32 v242, v62, v48, v56
	v_fma_f32 v243, v63, v49, v57
	v_lshlrev_b32_e32 v62, 16, v81
	v_and_b32_e32 v63, 0xffff0000, v81
	v_fma_f32 v244, v64, v48, v56
	v_fma_f32 v245, v65, v49, v57
	v_fma_f32 v242, v64, v50, v242
	v_fma_f32 v243, v65, v51, v243
	v_fma_f32 v244, v58, v50, v244
	v_fma_f32 v245, v59, v51, v245
	v_fma_f32 v242, v58, v52, v242
	v_fma_f32 v243, v59, v53, v243
	v_fma_f32 v244, v60, v52, v244
	v_fma_f32 v245, v61, v53, v245
	v_fma_f32 v242, v60, v54, v242
	v_fma_f32 v243, v61, v55, v243
	v_fma_f32 v244, v62, v54, v244
	v_fma_f32 v245, v63, v55, v245
	ds_write_b64 v226, v[242:243] offset:5600
	v_cvt_pk_bf16_f32 v246, v242, v243
	ds_write_b64 v226, v[244:245] offset:6000
	v_cvt_pk_bf16_f32 v247, v244, v245
	ds_write_b32 v227, v246 offset:2912
	ds_write_b32 v227, v247 offset:3120
	s_mov_b64 exec, -1
	s_waitcnt lgkmcnt(0)
	ds_read_b128 v[98:101], v228 offset:0
	ds_read_b128 v[102:105], v228 offset:64
	ds_read_b128 v[106:109], v228 offset:128
	ds_read_b128 v[162:165], v231
	s_waitcnt lgkmcnt(0)
	v_mfma_f32_16x16x32_bf16 v[134:137], v[110:113], v[98:101], 0
	v_mfma_f32_16x16x32_bf16 v[138:141], v[122:125], v[98:101], 0
	v_mfma_f32_16x16x32_bf16 v[134:137], v[114:117], v[102:105], v[134:137]
	v_mfma_f32_16x16x32_bf16 v[138:141], v[126:129], v[102:105], v[138:141]
	v_mfma_f32_16x16x32_bf16 v[134:137], v[118:121], v[106:109], v[134:137]
	v_mfma_f32_16x16x32_bf16 v[138:141], v[130:133], v[106:109], v[138:141]
	ds_read_b128 v[110:113], v229 offset:3328
	ds_read_b128 v[122:125], v229 offset:23296
	ds_read_b128 v[114:117], v229 offset:3392
	ds_read_b128 v[126:129], v229 offset:23360
	ds_read_b128 v[118:121], v229 offset:3456
	ds_read_b128 v[130:133], v229 offset:23424
	s_nop 7
	s_nop 7
	v_fmamk_f32 v166, v134, 0xbfb8aa3b, v150
	v_fmamk_f32 v204, v135, 0xbfb8aa3b, v151
	v_fmamk_f32 v210, v136, 0xbfb8aa3b, v152
	v_fmamk_f32 v216, v137, 0xbfb8aa3b, v153
	v_fmamk_f32 v167, v138, 0xbfb8aa3b, v154
	v_fmamk_f32 v205, v139, 0xbfb8aa3b, v155
	v_fmamk_f32 v211, v140, 0xbfb8aa3b, v156
	v_fmamk_f32 v217, v141, 0xbfb8aa3b, v157
	v_exp_f32_e32 v166, v166
	v_exp_f32_e32 v204, v204
	v_exp_f32_e32 v210, v210
	v_exp_f32_e32 v216, v216
	v_exp_f32_e32 v167, v167
	v_exp_f32_e32 v205, v205
	v_exp_f32_e32 v211, v211
	v_exp_f32_e32 v217, v217
	v_add_f32_e32 v166, 1.0, v166
	v_add_f32_e32 v204, 1.0, v204
	v_add_f32_e32 v210, 1.0, v210
	v_add_f32_e32 v216, 1.0, v216
	v_add_f32_e32 v167, 1.0, v167
	v_add_f32_e32 v205, 1.0, v205
	v_add_f32_e32 v211, 1.0, v211
	v_add_f32_e32 v217, 1.0, v217
	v_rcp_f32_e32 v166, v166
	v_rcp_f32_e32 v204, v204
	v_rcp_f32_e32 v210, v210
	v_rcp_f32_e32 v216, v216
	v_rcp_f32_e32 v167, v167
	v_rcp_f32_e32 v205, v205
	v_rcp_f32_e32 v211, v211
	v_rcp_f32_e32 v217, v217
	v_mul_f32_e32 v168, v158, v166
	v_mul_f32_e32 v206, v159, v204
	v_mul_f32_e32 v212, v160, v210
	v_mul_f32_e32 v218, v161, v216
	v_mul_f32_e32 v167, v162, v167
	v_mul_f32_e32 v205, v163, v205
	v_mul_f32_e32 v211, v164, v211
	v_mul_f32_e32 v217, v165, v217
	ds_read_b128 v[150:153], v230 offset:64
	ds_read_b128 v[154:157], v230 offset:448
	ds_read_b128 v[158:161], v230 offset:832
	ds_read_b128 v[162:165], v231 offset:64
	v_exp_f32_e32 v166, v168
	v_exp_f32_e32 v204, v206
	v_exp_f32_e32 v210, v212
	v_exp_f32_e32 v216, v218
	v_fmaak_f32 v170, v168, v248, 0xbe1d955b
	v_fmaak_f32 v208, v206, v248, 0xbe1d955b
	v_fmaak_f32 v214, v212, v248, 0xbe1d955b
	v_fmaak_f32 v220, v218, v248, 0xbe1d955b
	v_fmaak_f32 v170, v168, v170, 0xbee35847
	v_fmaak_f32 v208, v206, v208, 0xbee35847
	v_fmaak_f32 v214, v212, v214, 0xbee35847
	v_fmaak_f32 v220, v218, v220, 0xbee35847
	v_min3_f32 v169, v168, v206, v212
	v_fmaak_f32 v170, v168, v170, 0xbf75fdf0
	v_fmaak_f32 v208, v206, v208, 0xbf75fdf0
	v_fmaak_f32 v214, v212, v214, 0xbf75fdf0
	v_fmaak_f32 v220, v218, v220, 0xbf75fdf0
	v_min_f32_e32 v169, v169, v218
	v_fmaak_f32 v170, v168, v170, 0xbfb17218
	v_fmaak_f32 v208, v206, v208, 0xbfb17218
	v_fmaak_f32 v214, v212, v214, 0xbfb17218
	v_fmaak_f32 v220, v218, v220, 0xbfb17218
	v_cmp_nlt_f32_e32 vcc, 0xbe38aa3b, v169
	v_mul_f32_e32 v170, v170, v168
	v_mul_f32_e32 v208, v208, v206
	v_mul_f32_e32 v214, v214, v212
	v_mul_f32_e32 v220, v220, v218
	s_cbranch_vccnz .Lscan2_far0
.Lscan2_back0:
	v_sqrt_f32_e32 v170, v170
	v_sqrt_f32_e32 v208, v208
	v_sqrt_f32_e32 v214, v214
	v_sqrt_f32_e32 v220, v220
	v_mul_f32_e32 v167, v167, v170
	v_mul_f32_e32 v205, v205, v208
	v_mul_f32_e32 v211, v211, v214
	v_mul_f32_e32 v217, v217, v220
	s_waitcnt lgkmcnt(0)
	v_mfma_f32_16x16x32_bf16 v[142:145], v[110:113], v[98:101], 0
	v_mfma_f32_16x16x32_bf16 v[146:149], v[122:125], v[98:101], 0
	v_mfma_f32_16x16x32_bf16 v[142:145], v[114:117], v[102:105], v[142:145]
	v_mfma_f32_16x16x32_bf16 v[146:149], v[126:129], v[102:105], v[146:149]
	v_mfma_f32_16x16x32_bf16 v[142:145], v[118:121], v[106:109], v[142:145]
	v_mfma_f32_16x16x32_bf16 v[146:149], v[130:133], v[106:109], v[146:149]
	v_fmac_f32_dpp v167, v167, v166 row_shr:1 row_mask:0xf bank_mask:0xf bound_ctrl:1
	v_fmac_f32_dpp v205, v205, v204 row_shr:1 row_mask:0xf bank_mask:0xf bound_ctrl:1
	v_fmac_f32_dpp v211, v211, v210 row_shr:1 row_mask:0xf bank_mask:0xf bound_ctrl:1
	v_fmac_f32_dpp v217, v217, v216 row_shr:1 row_mask:0xf bank_mask:0xf bound_ctrl:1
	v_mul_f32_dpp v166, v166, v166 row_shr:1 row_mask:0xf bank_mask:0xf
	v_mul_f32_dpp v204, v204, v204 row_shr:1 row_mask:0xf bank_mask:0xf
	v_mul_f32_dpp v210, v210, v210 row_shr:1 row_mask:0xf bank_mask:0xf
	v_mul_f32_dpp v216, v216, v216 row_shr:1 row_mask:0xf bank_mask:0xf
	v_fmac_f32_dpp v167, v167, v166 row_shr:2 row_mask:0xf bank_mask:0xf bound_ctrl:1
	v_fmac_f32_dpp v205, v205, v204 row_shr:2 row_mask:0xf bank_mask:0xf bound_ctrl:1
	v_fmac_f32_dpp v211, v211, v210 row_shr:2 row_mask:0xf bank_mask:0xf bound_ctrl:1
	v_fmac_f32_dpp v217, v217, v216 row_shr:2 row_mask:0xf bank_mask:0xf bound_ctrl:1
	v_mul_f32_dpp v166, v166, v166 row_shr:2 row_mask:0xf bank_mask:0xf
	v_mul_f32_dpp v204, v204, v204 row_shr:2 row_mask:0xf bank_mask:0xf
	v_mul_f32_dpp v210, v210, v210 row_shr:2 row_mask:0xf bank_mask:0xf
	v_mul_f32_dpp v216, v216, v216 row_shr:2 row_mask:0xf bank_mask:0xf
	v_fmac_f32_dpp v167, v167, v166 row_shr:4 row_mask:0xf bank_mask:0xf bound_ctrl:1
	v_fmac_f32_dpp v205, v205, v204 row_shr:4 row_mask:0xf bank_mask:0xf bound_ctrl:1
	v_fmac_f32_dpp v211, v211, v210 row_shr:4 row_mask:0xf bank_mask:0xf bound_ctrl:1
	v_fmac_f32_dpp v217, v217, v216 row_shr:4 row_mask:0xf bank_mask:0xf bound_ctrl:1
	v_mul_f32_dpp v166, v166, v166 row_shr:4 row_mask:0xf bank_mask:0xf
	v_mul_f32_dpp v204, v204, v204 row_shr:4 row_mask:0xf bank_mask:0xf
	v_mul_f32_dpp v210, v210, v210 row_shr:4 row_mask:0xf bank_mask:0xf
	v_mul_f32_dpp v216, v216, v216 row_shr:4 row_mask:0xf bank_mask:0xf
	v_fmac_f32_dpp v167, v167, v166 row_shr:8 row_mask:0xf bank_mask:0xf bound_ctrl:1
	v_fmac_f32_dpp v205, v205, v204 row_shr:8 row_mask:0xf bank_mask:0xf bound_ctrl:1
	v_fmac_f32_dpp v211, v211, v210 row_shr:8 row_mask:0xf bank_mask:0xf bound_ctrl:1
	v_fmac_f32_dpp v217, v217, v216 row_shr:8 row_mask:0xf bank_mask:0xf bound_ctrl:1
	v_mul_f32_dpp v166, v166, v166 row_shr:8 row_mask:0xf bank_mask:0xf
	v_mul_f32_dpp v204, v204, v204 row_shr:8 row_mask:0xf bank_mask:0xf
	v_mul_f32_dpp v210, v210, v210 row_shr:8 row_mask:0xf bank_mask:0xf
	v_mul_f32_dpp v216, v216, v216 row_shr:8 row_mask:0xf bank_mask:0xf
	v_fma_f32 v168, v166, v0, v167
	v_fma_f32 v206, v204, v1, v205
	v_fma_f32 v212, v210, v2, v211
	v_fma_f32 v218, v216, v3, v217
	ds_bpermute_b32 v0, v232, v168
	ds_bpermute_b32 v1, v232, v206
	ds_bpermute_b32 v2, v232, v212
	ds_bpermute_b32 v3, v232, v218
	s_waitcnt vmcnt(21)
	v_lshlrev_b32_e32 v169, 16, v24
	v_and_b32_e32 v207, 0xffff0000, v24
	v_lshlrev_b32_e32 v213, 16, v25
	v_and_b32_e32 v219, 0xffff0000, v25
	v_mul_f32_e32 v170, v169, v169
	v_mul_f32_e32 v208, v207, v207
	v_mul_f32_e32 v214, v213, v213
	v_mul_f32_e32 v220, v219, v219
	v_fmaak_f32 v170, v170, v249, 0xc0135761
	v_fmaak_f32 v208, v208, v249, 0xc0135761
	v_fmaak_f32 v214, v214, v249, 0xc0135761
	v_fmaak_f32 v220, v220, v249, 0xc0135761
	v_mul_f32_e32 v170, v169, v170
	v_mul_f32_e32 v208, v207, v208
	v_mul_f32_e32 v214, v213, v214
	v_mul_f32_e32 v220, v219, v220
	v_exp_f32_e32 v170, v170
	v_exp_f32_e32 v208, v208
	v_exp_f32_e32 v214, v214
	v_exp_f32_e32 v220, v220
	v_add_f32_e32 v170, 1.0, v170
	v_add_f32_e32 v208, 1.0, v208
	v_add_f32_e32 v214, 1.0, v214
	v_add_f32_e32 v220, 1.0, v220
	v_rcp_f32_e32 v170, v170
	v_rcp_f32_e32 v208, v208
	v_rcp_f32_e32 v214, v214
	v_rcp_f32_e32 v220, v220
	v_mul_f32_e32 v170, v169, v170
	v_mul_f32_e32 v208, v207, v208
	v_mul_f32_e32 v214, v213, v214
	v_mul_f32_e32 v220, v219, v220
	v_mul_f32_e32 v170, v170, v168
	v_mul_f32_e32 v208, v208, v206
	v_mul_f32_e32 v214, v214, v212
	v_mul_f32_e32 v220, v220, v218
	v_cvt_pk_bf16_f32 v242, v170, v208
	v_cvt_pk_bf16_f32 v243, v214, v220
	global_store_dwordx2 v236, v[242:243], s[100:101] offset:0
	ds_read_b128 v[110:113], v229 offset:6656
	ds_read_b128 v[122:125], v229 offset:26624
	ds_read_b128 v[114:117], v229 offset:6720
	ds_read_b128 v[126:129], v229 offset:26688
	ds_read_b128 v[118:121], v229 offset:6784
	ds_read_b128 v[130:133], v229 offset:26752
	v_fmamk_f32 v166, v142, 0xbfb8aa3b, v150
	v_fmamk_f32 v204, v143, 0xbfb8aa3b, v151
	v_fmamk_f32 v210, v144, 0xbfb8aa3b, v152
	v_fmamk_f32 v216, v145, 0xbfb8aa3b, v153
	v_fmamk_f32 v167, v146, 0xbfb8aa3b, v154
	v_fmamk_f32 v205, v147, 0xbfb8aa3b, v155
	v_fmamk_f32 v211, v148, 0xbfb8aa3b, v156
	v_fmamk_f32 v217, v149, 0xbfb8aa3b, v157
	v_exp_f32_e32 v166, v166
	v_exp_f32_e32 v204, v204
	v_exp_f32_e32 v210, v210
	v_exp_f32_e32 v216, v216
	v_exp_f32_e32 v167, v167
	v_exp_f32_e32 v205, v205
	v_exp_f32_e32 v211, v211
	v_exp_f32_e32 v217, v217
	v_add_f32_e32 v166, 1.0, v166
	v_add_f32_e32 v204, 1.0, v204
	v_add_f32_e32 v210, 1.0, v210
	v_add_f32_e32 v216, 1.0, v216
	v_add_f32_e32 v167, 1.0, v167
	v_add_f32_e32 v205, 1.0, v205
	v_add_f32_e32 v211, 1.0, v211
	v_add_f32_e32 v217, 1.0, v217
	v_rcp_f32_e32 v166, v166
	v_rcp_f32_e32 v204, v204
	v_rcp_f32_e32 v210, v210
	v_rcp_f32_e32 v216, v216
	v_rcp_f32_e32 v167, v167
	v_rcp_f32_e32 v205, v205
	v_rcp_f32_e32 v211, v211
	v_rcp_f32_e32 v217, v217
	v_mul_f32_e32 v168, v158, v166
	v_mul_f32_e32 v206, v159, v204
	v_mul_f32_e32 v212, v160, v210
	v_mul_f32_e32 v218, v161, v216
	v_mul_f32_e32 v167, v162, v167
	v_mul_f32_e32 v205, v163, v205
	v_mul_f32_e32 v211, v164, v211
	v_mul_f32_e32 v217, v165, v217
	ds_read_b128 v[150:153], v230 offset:128
	ds_read_b128 v[154:157], v230 offset:512
	ds_read_b128 v[158:161], v230 offset:896
	ds_read_b128 v[162:165], v231 offset:128
	v_exp_f32_e32 v166, v168
	v_exp_f32_e32 v204, v206
	v_exp_f32_e32 v210, v212
	v_exp_f32_e32 v216, v218
	v_fmaak_f32 v170, v168, v248, 0xbe1d955b
	v_fmaak_f32 v208, v206, v248, 0xbe1d955b
	v_fmaak_f32 v214, v212, v248, 0xbe1d955b
	v_fmaak_f32 v220, v218, v248, 0xbe1d955b
	v_fmaak_f32 v170, v168, v170, 0xbee35847
	v_fmaak_f32 v208, v206, v208, 0xbee35847
	v_fmaak_f32 v214, v212, v214, 0xbee35847
	v_fmaak_f32 v220, v218, v220, 0xbee35847
	v_min3_f32 v169, v168, v206, v212
	v_fmaak_f32 v170, v168, v170, 0xbf75fdf0
	v_fmaak_f32 v208, v206, v208, 0xbf75fdf0
	v_fmaak_f32 v214, v212, v214, 0xbf75fdf0
	v_fmaak_f32 v220, v218, v220, 0xbf75fdf0
	v_min_f32_e32 v169, v169, v218
	v_fmaak_f32 v170, v168, v170, 0xbfb17218
	v_fmaak_f32 v208, v206, v208, 0xbfb17218
	v_fmaak_f32 v214, v212, v214, 0xbfb17218
	v_fmaak_f32 v220, v218, v220, 0xbfb17218
	v_cmp_nlt_f32_e32 vcc, 0xbe38aa3b, v169
	v_mul_f32_e32 v170, v170, v168
	v_mul_f32_e32 v208, v208, v206
	v_mul_f32_e32 v214, v214, v212
	v_mul_f32_e32 v220, v220, v218
	s_cbranch_vccnz .Lscan2_far1
.Lscan2_back1:
	v_sqrt_f32_e32 v170, v170
	v_sqrt_f32_e32 v208, v208
	v_sqrt_f32_e32 v214, v214
	v_sqrt_f32_e32 v220, v220
	v_mul_f32_e32 v167, v167, v170
	v_mul_f32_e32 v205, v205, v208
	v_mul_f32_e32 v211, v211, v214
	v_mul_f32_e32 v217, v217, v220
	s_waitcnt lgkmcnt(0)
	v_mfma_f32_16x16x32_bf16 v[134:137], v[110:113], v[98:101], 0
	v_mfma_f32_16x16x32_bf16 v[138:141], v[122:125], v[98:101], 0
	v_mfma_f32_16x16x32_bf16 v[134:137], v[114:117], v[102:105], v[134:137]
	v_mfma_f32_16x16x32_bf16 v[138:141], v[126:129], v[102:105], v[138:141]
	v_mfma_f32_16x16x32_bf16 v[134:137], v[118:121], v[106:109], v[134:137]
	v_mfma_f32_16x16x32_bf16 v[138:141], v[130:133], v[106:109], v[138:141]
	v_fmac_f32_dpp v167, v167, v166 row_shr:1 row_mask:0xf bank_mask:0xf bound_ctrl:1
	v_fmac_f32_dpp v205, v205, v204 row_shr:1 row_mask:0xf bank_mask:0xf bound_ctrl:1
	v_fmac_f32_dpp v211, v211, v210 row_shr:1 row_mask:0xf bank_mask:0xf bound_ctrl:1
	v_fmac_f32_dpp v217, v217, v216 row_shr:1 row_mask:0xf bank_mask:0xf bound_ctrl:1
	v_mul_f32_dpp v166, v166, v166 row_shr:1 row_mask:0xf bank_mask:0xf
	v_mul_f32_dpp v204, v204, v204 row_shr:1 row_mask:0xf bank_mask:0xf
	v_mul_f32_dpp v210, v210, v210 row_shr:1 row_mask:0xf bank_mask:0xf
	v_mul_f32_dpp v216, v216, v216 row_shr:1 row_mask:0xf bank_mask:0xf
	v_fmac_f32_dpp v167, v167, v166 row_shr:2 row_mask:0xf bank_mask:0xf bound_ctrl:1
	v_fmac_f32_dpp v205, v205, v204 row_shr:2 row_mask:0xf bank_mask:0xf bound_ctrl:1
	v_fmac_f32_dpp v211, v211, v210 row_shr:2 row_mask:0xf bank_mask:0xf bound_ctrl:1
	v_fmac_f32_dpp v217, v217, v216 row_shr:2 row_mask:0xf bank_mask:0xf bound_ctrl:1
	v_mul_f32_dpp v166, v166, v166 row_shr:2 row_mask:0xf bank_mask:0xf
	v_mul_f32_dpp v204, v204, v204 row_shr:2 row_mask:0xf bank_mask:0xf
	v_mul_f32_dpp v210, v210, v210 row_shr:2 row_mask:0xf bank_mask:0xf
	v_mul_f32_dpp v216, v216, v216 row_shr:2 row_mask:0xf bank_mask:0xf
	v_fmac_f32_dpp v167, v167, v166 row_shr:4 row_mask:0xf bank_mask:0xf bound_ctrl:1
	v_fmac_f32_dpp v205, v205, v204 row_shr:4 row_mask:0xf bank_mask:0xf bound_ctrl:1
	v_fmac_f32_dpp v211, v211, v210 row_shr:4 row_mask:0xf bank_mask:0xf bound_ctrl:1
	v_fmac_f32_dpp v217, v217, v216 row_shr:4 row_mask:0xf bank_mask:0xf bound_ctrl:1
	v_mul_f32_dpp v166, v166, v166 row_shr:4 row_mask:0xf bank_mask:0xf
	v_mul_f32_dpp v204, v204, v204 row_shr:4 row_mask:0xf bank_mask:0xf
	v_mul_f32_dpp v210, v210, v210 row_shr:4 row_mask:0xf bank_mask:0xf
	v_mul_f32_dpp v216, v216, v216 row_shr:4 row_mask:0xf bank_mask:0xf
	v_fmac_f32_dpp v167, v167, v166 row_shr:8 row_mask:0xf bank_mask:0xf bound_ctrl:1
	v_fmac_f32_dpp v205, v205, v204 row_shr:8 row_mask:0xf bank_mask:0xf bound_ctrl:1
	v_fmac_f32_dpp v211, v211, v210 row_shr:8 row_mask:0xf bank_mask:0xf bound_ctrl:1
	v_fmac_f32_dpp v217, v217, v216 row_shr:8 row_mask:0xf bank_mask:0xf bound_ctrl:1
	v_mul_f32_dpp v166, v166, v166 row_shr:8 row_mask:0xf bank_mask:0xf
	v_mul_f32_dpp v204, v204, v204 row_shr:8 row_mask:0xf bank_mask:0xf
	v_mul_f32_dpp v210, v210, v210 row_shr:8 row_mask:0xf bank_mask:0xf
	v_mul_f32_dpp v216, v216, v216 row_shr:8 row_mask:0xf bank_mask:0xf
	v_fma_f32 v168, v166, v4, v167
	v_fma_f32 v206, v204, v5, v205
	v_fma_f32 v212, v210, v6, v211
	v_fma_f32 v218, v216, v7, v217
	ds_bpermute_b32 v4, v232, v168
	ds_bpermute_b32 v5, v232, v206
	ds_bpermute_b32 v6, v232, v212
	ds_bpermute_b32 v7, v232, v218
	s_waitcnt vmcnt(21)
	v_lshlrev_b32_e32 v169, 16, v26
	v_and_b32_e32 v207, 0xffff0000, v26
	v_lshlrev_b32_e32 v213, 16, v27
	v_and_b32_e32 v219, 0xffff0000, v27
	v_mul_f32_e32 v170, v169, v169
	v_mul_f32_e32 v208, v207, v207
	v_mul_f32_e32 v214, v213, v213
	v_mul_f32_e32 v220, v219, v219
	v_fmaak_f32 v170, v170, v249, 0xc0135761
	v_fmaak_f32 v208, v208, v249, 0xc0135761
	v_fmaak_f32 v214, v214, v249, 0xc0135761
	v_fmaak_f32 v220, v220, v249, 0xc0135761
	v_mul_f32_e32 v170, v169, v170
	v_mul_f32_e32 v208, v207, v208
	v_mul_f32_e32 v214, v213, v214
	v_mul_f32_e32 v220, v219, v220
	v_exp_f32_e32 v170, v170
	v_exp_f32_e32 v208, v208
	v_exp_f32_e32 v214, v214
	v_exp_f32_e32 v220, v220
	v_add_f32_e32 v170, 1.0, v170
	v_add_f32_e32 v208, 1.0, v208
	v_add_f32_e32 v214, 1.0, v214
	v_add_f32_e32 v220, 1.0, v220
	v_rcp_f32_e32 v170, v170
	v_rcp_f32_e32 v208, v208
	v_rcp_f32_e32 v214, v214
	v_rcp_f32_e32 v220, v220
	v_mul_f32_e32 v170, v169, v170
	v_mul_f32_e32 v208, v207, v208
	v_mul_f32_e32 v214, v213, v214
	v_mul_f32_e32 v220, v219, v220
	v_mul_f32_e32 v170, v170, v168
	v_mul_f32_e32 v208, v208, v206
	v_mul_f32_e32 v214, v214, v212
	v_mul_f32_e32 v220, v220, v218
	v_cvt_pk_bf16_f32 v242, v170, v208
	v_cvt_pk_bf16_f32 v243, v214, v220
	global_store_dwordx2 v236, v[242:243], s[100:101] offset:32
	ds_read_b128 v[110:113], v229 offset:9984
	ds_read_b128 v[122:125], v229 offset:29952
	ds_read_b128 v[114:117], v229 offset:10048
	ds_read_b128 v[126:129], v229 offset:30016
	ds_read_b128 v[118:121], v229 offset:10112
	ds_read_b128 v[130:133], v229 offset:30080
	v_fmamk_f32 v166, v134, 0xbfb8aa3b, v150
	v_fmamk_f32 v204, v135, 0xbfb8aa3b, v151
	v_fmamk_f32 v210, v136, 0xbfb8aa3b, v152
	v_fmamk_f32 v216, v137, 0xbfb8aa3b, v153
	v_fmamk_f32 v167, v138, 0xbfb8aa3b, v154
	v_fmamk_f32 v205, v139, 0xbfb8aa3b, v155
	v_fmamk_f32 v211, v140, 0xbfb8aa3b, v156
	v_fmamk_f32 v217, v141, 0xbfb8aa3b, v157
	v_exp_f32_e32 v166, v166
	v_exp_f32_e32 v204, v204
	v_exp_f32_e32 v210, v210
	v_exp_f32_e32 v216, v216
	v_exp_f32_e32 v167, v167
	v_exp_f32_e32 v205, v205
	v_exp_f32_e32 v211, v211
	v_exp_f32_e32 v217, v217
	v_add_f32_e32 v166, 1.0, v166
	v_add_f32_e32 v204, 1.0, v204
	v_add_f32_e32 v210, 1.0, v210
	v_add_f32_e32 v216, 1.0, v216
	v_add_f32_e32 v167, 1.0, v167
	v_add_f32_e32 v205, 1.0, v205
	v_add_f32_e32 v211, 1.0, v211
	v_add_f32_e32 v217, 1.0, v217
	v_rcp_f32_e32 v166, v166
	v_rcp_f32_e32 v204, v204
	v_rcp_f32_e32 v210, v210
	v_rcp_f32_e32 v216, v216
	v_rcp_f32_e32 v167, v167
	v_rcp_f32_e32 v205, v205
	v_rcp_f32_e32 v211, v211
	v_rcp_f32_e32 v217, v217
	v_mul_f32_e32 v168, v158, v166
	v_mul_f32_e32 v206, v159, v204
	v_mul_f32_e32 v212, v160, v210
	v_mul_f32_e32 v218, v161, v216
	v_mul_f32_e32 v167, v162, v167
	v_mul_f32_e32 v205, v163, v205
	v_mul_f32_e32 v211, v164, v211
	v_mul_f32_e32 v217, v165, v217
	ds_read_b128 v[150:153], v230 offset:192
	ds_read_b128 v[154:157], v230 offset:576
	ds_read_b128 v[158:161], v230 offset:960
	ds_read_b128 v[162:165], v231 offset:192
	v_exp_f32_e32 v166, v168
	v_exp_f32_e32 v204, v206
	v_exp_f32_e32 v210, v212
	v_exp_f32_e32 v216, v218
	v_fmaak_f32 v170, v168, v248, 0xbe1d955b
	v_fmaak_f32 v208, v206, v248, 0xbe1d955b
	v_fmaak_f32 v214, v212, v248, 0xbe1d955b
	v_fmaak_f32 v220, v218, v248, 0xbe1d955b
	v_fmaak_f32 v170, v168, v170, 0xbee35847
	v_fmaak_f32 v208, v206, v208, 0xbee35847
	v_fmaak_f32 v214, v212, v214, 0xbee35847
	v_fmaak_f32 v220, v218, v220, 0xbee35847
	v_min3_f32 v169, v168, v206, v212
	v_fmaak_f32 v170, v168, v170, 0xbf75fdf0
	v_fmaak_f32 v208, v206, v208, 0xbf75fdf0
	v_fmaak_f32 v214, v212, v214, 0xbf75fdf0
	v_fmaak_f32 v220, v218, v220, 0xbf75fdf0
	v_min_f32_e32 v169, v169, v218
	v_fmaak_f32 v170, v168, v170, 0xbfb17218
	v_fmaak_f32 v208, v206, v208, 0xbfb17218
	v_fmaak_f32 v214, v212, v214, 0xbfb17218
	v_fmaak_f32 v220, v218, v220, 0xbfb17218
	v_cmp_nlt_f32_e32 vcc, 0xbe38aa3b, v169
	v_mul_f32_e32 v170, v170, v168
	v_mul_f32_e32 v208, v208, v206
	v_mul_f32_e32 v214, v214, v212
	v_mul_f32_e32 v220, v220, v218
	s_cbranch_vccnz .Lscan2_far2
.Lscan2_back2:
	v_sqrt_f32_e32 v170, v170
	v_sqrt_f32_e32 v208, v208
	v_sqrt_f32_e32 v214, v214
	v_sqrt_f32_e32 v220, v220
	v_mul_f32_e32 v167, v167, v170
	v_mul_f32_e32 v205, v205, v208
	v_mul_f32_e32 v211, v211, v214
	v_mul_f32_e32 v217, v217, v220
	s_waitcnt lgkmcnt(0)
	v_mfma_f32_16x16x32_bf16 v[142:145], v[110:113], v[98:101], 0
	v_mfma_f32_16x16x32_bf16 v[146:149], v[122:125], v[98:101], 0
	v_mfma_f32_16x16x32_bf16 v[142:145], v[114:117], v[102:105], v[142:145]
	v_mfma_f32_16x16x32_bf16 v[146:149], v[126:129], v[102:105], v[146:149]
	v_mfma_f32_16x16x32_bf16 v[142:145], v[118:121], v[106:109], v[142:145]
	v_mfma_f32_16x16x32_bf16 v[146:149], v[130:133], v[106:109], v[146:149]
	v_fmac_f32_dpp v167, v167, v166 row_shr:1 row_mask:0xf bank_mask:0xf bound_ctrl:1
	v_fmac_f32_dpp v205, v205, v204 row_shr:1 row_mask:0xf bank_mask:0xf bound_ctrl:1
	v_fmac_f32_dpp v211, v211, v210 row_shr:1 row_mask:0xf bank_mask:0xf bound_ctrl:1
	v_fmac_f32_dpp v217, v217, v216 row_shr:1 row_mask:0xf bank_mask:0xf bound_ctrl:1
	v_mul_f32_dpp v166, v166, v166 row_shr:1 row_mask:0xf bank_mask:0xf
	v_mul_f32_dpp v204, v204, v204 row_shr:1 row_mask:0xf bank_mask:0xf
	v_mul_f32_dpp v210, v210, v210 row_shr:1 row_mask:0xf bank_mask:0xf
	v_mul_f32_dpp v216, v216, v216 row_shr:1 row_mask:0xf bank_mask:0xf
	v_fmac_f32_dpp v167, v167, v166 row_shr:2 row_mask:0xf bank_mask:0xf bound_ctrl:1
	v_fmac_f32_dpp v205, v205, v204 row_shr:2 row_mask:0xf bank_mask:0xf bound_ctrl:1
	v_fmac_f32_dpp v211, v211, v210 row_shr:2 row_mask:0xf bank_mask:0xf bound_ctrl:1
	v_fmac_f32_dpp v217, v217, v216 row_shr:2 row_mask:0xf bank_mask:0xf bound_ctrl:1
	v_mul_f32_dpp v166, v166, v166 row_shr:2 row_mask:0xf bank_mask:0xf
	v_mul_f32_dpp v204, v204, v204 row_shr:2 row_mask:0xf bank_mask:0xf
	v_mul_f32_dpp v210, v210, v210 row_shr:2 row_mask:0xf bank_mask:0xf
	v_mul_f32_dpp v216, v216, v216 row_shr:2 row_mask:0xf bank_mask:0xf
	v_fmac_f32_dpp v167, v167, v166 row_shr:4 row_mask:0xf bank_mask:0xf bound_ctrl:1
	v_fmac_f32_dpp v205, v205, v204 row_shr:4 row_mask:0xf bank_mask:0xf bound_ctrl:1
	v_fmac_f32_dpp v211, v211, v210 row_shr:4 row_mask:0xf bank_mask:0xf bound_ctrl:1
	v_fmac_f32_dpp v217, v217, v216 row_shr:4 row_mask:0xf bank_mask:0xf bound_ctrl:1
	v_mul_f32_dpp v166, v166, v166 row_shr:4 row_mask:0xf bank_mask:0xf
	v_mul_f32_dpp v204, v204, v204 row_shr:4 row_mask:0xf bank_mask:0xf
	v_mul_f32_dpp v210, v210, v210 row_shr:4 row_mask:0xf bank_mask:0xf
	v_mul_f32_dpp v216, v216, v216 row_shr:4 row_mask:0xf bank_mask:0xf
	v_fmac_f32_dpp v167, v167, v166 row_shr:8 row_mask:0xf bank_mask:0xf bound_ctrl:1
	v_fmac_f32_dpp v205, v205, v204 row_shr:8 row_mask:0xf bank_mask:0xf bound_ctrl:1
	v_fmac_f32_dpp v211, v211, v210 row_shr:8 row_mask:0xf bank_mask:0xf bound_ctrl:1
	v_fmac_f32_dpp v217, v217, v216 row_shr:8 row_mask:0xf bank_mask:0xf bound_ctrl:1
	v_mul_f32_dpp v166, v166, v166 row_shr:8 row_mask:0xf bank_mask:0xf
	v_mul_f32_dpp v204, v204, v204 row_shr:8 row_mask:0xf bank_mask:0xf
	v_mul_f32_dpp v210, v210, v210 row_shr:8 row_mask:0xf bank_mask:0xf
	v_mul_f32_dpp v216, v216, v216 row_shr:8 row_mask:0xf bank_mask:0xf
	v_fma_f32 v168, v166, v8, v167
	v_fma_f32 v206, v204, v9, v205
	v_fma_f32 v212, v210, v10, v211
	v_fma_f32 v218, v216, v11, v217
	ds_bpermute_b32 v8, v232, v168
	ds_bpermute_b32 v9, v232, v206
	ds_bpermute_b32 v10, v232, v212
	ds_bpermute_b32 v11, v232, v218
	s_waitcnt vmcnt(21)
	v_lshlrev_b32_e32 v169, 16, v28
	v_and_b32_e32 v207, 0xffff0000, v28
	v_lshlrev_b32_e32 v213, 16, v29
	v_and_b32_e32 v219, 0xffff0000, v29
	v_mul_f32_e32 v170, v169, v169
	v_mul_f32_e32 v208, v207, v207
	v_mul_f32_e32 v214, v213, v213
	v_mul_f32_e32 v220, v219, v219
	v_fmaak_f32 v170, v170, v249, 0xc0135761
	v_fmaak_f32 v208, v208, v249, 0xc0135761
	v_fmaak_f32 v214, v214, v249, 0xc0135761
	v_fmaak_f32 v220, v220, v249, 0xc0135761
	v_mul_f32_e32 v170, v169, v170
	v_mul_f32_e32 v208, v207, v208
	v_mul_f32_e32 v214, v213, v214
	v_mul_f32_e32 v220, v219, v220
	v_exp_f32_e32 v170, v170
	v_exp_f32_e32 v208, v208
	v_exp_f32_e32 v214, v214
	v_exp_f32_e32 v220, v220
	v_add_f32_e32 v170, 1.0, v170
	v_add_f32_e32 v208, 1.0, v208
	v_add_f32_e32 v214, 1.0, v214
	v_add_f32_e32 v220, 1.0, v220
	v_rcp_f32_e32 v170, v170
	v_rcp_f32_e32 v208, v208
	v_rcp_f32_e32 v214, v214
	v_rcp_f32_e32 v220, v220
	v_mul_f32_e32 v170, v169, v170
	v_mul_f32_e32 v208, v207, v208
	v_mul_f32_e32 v214, v213, v214
	v_mul_f32_e32 v220, v219, v220
	v_mul_f32_e32 v170, v170, v168
	v_mul_f32_e32 v208, v208, v206
	v_mul_f32_e32 v214, v214, v212
	v_mul_f32_e32 v220, v220, v218
	v_cvt_pk_bf16_f32 v242, v170, v208
	v_cvt_pk_bf16_f32 v243, v214, v220
	global_store_dwordx2 v236, v[242:243], s[100:101] offset:64
	ds_read_b128 v[110:113], v229 offset:13312
	ds_read_b128 v[122:125], v229 offset:33280
	ds_read_b128 v[114:117], v229 offset:13376
	ds_read_b128 v[126:129], v229 offset:33344
	ds_read_b128 v[118:121], v229 offset:13440
	ds_read_b128 v[130:133], v229 offset:33408
	v_fmamk_f32 v166, v142, 0xbfb8aa3b, v150
	v_fmamk_f32 v204, v143, 0xbfb8aa3b, v151
	v_fmamk_f32 v210, v144, 0xbfb8aa3b, v152
	v_fmamk_f32 v216, v145, 0xbfb8aa3b, v153
	v_fmamk_f32 v167, v146, 0xbfb8aa3b, v154
	v_fmamk_f32 v205, v147, 0xbfb8aa3b, v155
	v_fmamk_f32 v211, v148, 0xbfb8aa3b, v156
	v_fmamk_f32 v217, v149, 0xbfb8aa3b, v157
	v_exp_f32_e32 v166, v166
	v_exp_f32_e32 v204, v204
	v_exp_f32_e32 v210, v210
	v_exp_f32_e32 v216, v216
	v_exp_f32_e32 v167, v167
	v_exp_f32_e32 v205, v205
	v_exp_f32_e32 v211, v211
	v_exp_f32_e32 v217, v217
	v_add_f32_e32 v166, 1.0, v166
	v_add_f32_e32 v204, 1.0, v204
	v_add_f32_e32 v210, 1.0, v210
	v_add_f32_e32 v216, 1.0, v216
	v_add_f32_e32 v167, 1.0, v167
	v_add_f32_e32 v205, 1.0, v205
	v_add_f32_e32 v211, 1.0, v211
	v_add_f32_e32 v217, 1.0, v217
	v_rcp_f32_e32 v166, v166
	v_rcp_f32_e32 v204, v204
	v_rcp_f32_e32 v210, v210
	v_rcp_f32_e32 v216, v216
	v_rcp_f32_e32 v167, v167
	v_rcp_f32_e32 v205, v205
	v_rcp_f32_e32 v211, v211
	v_rcp_f32_e32 v217, v217
	v_mul_f32_e32 v168, v158, v166
	v_mul_f32_e32 v206, v159, v204
	v_mul_f32_e32 v212, v160, v210
	v_mul_f32_e32 v218, v161, v216
	v_mul_f32_e32 v167, v162, v167
	v_mul_f32_e32 v205, v163, v205
	v_mul_f32_e32 v211, v164, v211
	v_mul_f32_e32 v217, v165, v217
	ds_read_b128 v[150:153], v230 offset:256
	ds_read_b128 v[154:157], v230 offset:640
	ds_read_b128 v[158:161], v230 offset:1024
	ds_read_b128 v[162:165], v231 offset:256
	v_exp_f32_e32 v166, v168
	v_exp_f32_e32 v204, v206
	v_exp_f32_e32 v210, v212
	v_exp_f32_e32 v216, v218
	v_fmaak_f32 v170, v168, v248, 0xbe1d955b
	v_fmaak_f32 v208, v206, v248, 0xbe1d955b
	v_fmaak_f32 v214, v212, v248, 0xbe1d955b
	v_fmaak_f32 v220, v218, v248, 0xbe1d955b
	v_fmaak_f32 v170, v168, v170, 0xbee35847
	v_fmaak_f32 v208, v206, v208, 0xbee35847
	v_fmaak_f32 v214, v212, v214, 0xbee35847
	v_fmaak_f32 v220, v218, v220, 0xbee35847
	v_min3_f32 v169, v168, v206, v212
	v_fmaak_f32 v170, v168, v170, 0xbf75fdf0
	v_fmaak_f32 v208, v206, v208, 0xbf75fdf0
	v_fmaak_f32 v214, v212, v214, 0xbf75fdf0
	v_fmaak_f32 v220, v218, v220, 0xbf75fdf0
	v_min_f32_e32 v169, v169, v218
	v_fmaak_f32 v170, v168, v170, 0xbfb17218
	v_fmaak_f32 v208, v206, v208, 0xbfb17218
	v_fmaak_f32 v214, v212, v214, 0xbfb17218
	v_fmaak_f32 v220, v218, v220, 0xbfb17218
	v_cmp_nlt_f32_e32 vcc, 0xbe38aa3b, v169
	v_mul_f32_e32 v170, v170, v168
	v_mul_f32_e32 v208, v208, v206
	v_mul_f32_e32 v214, v214, v212
	v_mul_f32_e32 v220, v220, v218
	s_cbranch_vccnz .Lscan2_far3
.Lscan2_back3:
	v_sqrt_f32_e32 v170, v170
	v_sqrt_f32_e32 v208, v208
	v_sqrt_f32_e32 v214, v214
	v_sqrt_f32_e32 v220, v220
	v_mul_f32_e32 v167, v167, v170
	v_mul_f32_e32 v205, v205, v208
	v_mul_f32_e32 v211, v211, v214
	v_mul_f32_e32 v217, v217, v220
	s_waitcnt lgkmcnt(0)
	v_mfma_f32_16x16x32_bf16 v[134:137], v[110:113], v[98:101], 0
	v_mfma_f32_16x16x32_bf16 v[138:141], v[122:125], v[98:101], 0
	v_mfma_f32_16x16x32_bf16 v[134:137], v[114:117], v[102:105], v[134:137]
	v_mfma_f32_16x16x32_bf16 v[138:141], v[126:129], v[102:105], v[138:141]
	v_mfma_f32_16x16x32_bf16 v[134:137], v[118:121], v[106:109], v[134:137]
	v_mfma_f32_16x16x32_bf16 v[138:141], v[130:133], v[106:109], v[138:141]
	v_fmac_f32_dpp v167, v167, v166 row_shr:1 row_mask:0xf bank_mask:0xf bound_ctrl:1
	v_fmac_f32_dpp v205, v205, v204 row_shr:1 row_mask:0xf bank_mask:0xf bound_ctrl:1
	v_fmac_f32_dpp v211, v211, v210 row_shr:1 row_mask:0xf bank_mask:0xf bound_ctrl:1
	v_fmac_f32_dpp v217, v217, v216 row_shr:1 row_mask:0xf bank_mask:0xf bound_ctrl:1
	v_mul_f32_dpp v166, v166, v166 row_shr:1 row_mask:0xf bank_mask:0xf
	v_mul_f32_dpp v204, v204, v204 row_shr:1 row_mask:0xf bank_mask:0xf
	v_mul_f32_dpp v210, v210, v210 row_shr:1 row_mask:0xf bank_mask:0xf
	v_mul_f32_dpp v216, v216, v216 row_shr:1 row_mask:0xf bank_mask:0xf
	v_fmac_f32_dpp v167, v167, v166 row_shr:2 row_mask:0xf bank_mask:0xf bound_ctrl:1
	v_fmac_f32_dpp v205, v205, v204 row_shr:2 row_mask:0xf bank_mask:0xf bound_ctrl:1
	v_fmac_f32_dpp v211, v211, v210 row_shr:2 row_mask:0xf bank_mask:0xf bound_ctrl:1
	v_fmac_f32_dpp v217, v217, v216 row_shr:2 row_mask:0xf bank_mask:0xf bound_ctrl:1
	v_mul_f32_dpp v166, v166, v166 row_shr:2 row_mask:0xf bank_mask:0xf
	v_mul_f32_dpp v204, v204, v204 row_shr:2 row_mask:0xf bank_mask:0xf
	v_mul_f32_dpp v210, v210, v210 row_shr:2 row_mask:0xf bank_mask:0xf
	v_mul_f32_dpp v216, v216, v216 row_shr:2 row_mask:0xf bank_mask:0xf
	v_fmac_f32_dpp v167, v167, v166 row_shr:4 row_mask:0xf bank_mask:0xf bound_ctrl:1
	v_fmac_f32_dpp v205, v205, v204 row_shr:4 row_mask:0xf bank_mask:0xf bound_ctrl:1
	v_fmac_f32_dpp v211, v211, v210 row_shr:4 row_mask:0xf bank_mask:0xf bound_ctrl:1
	v_fmac_f32_dpp v217, v217, v216 row_shr:4 row_mask:0xf bank_mask:0xf bound_ctrl:1
	v_mul_f32_dpp v166, v166, v166 row_shr:4 row_mask:0xf bank_mask:0xf
	v_mul_f32_dpp v204, v204, v204 row_shr:4 row_mask:0xf bank_mask:0xf
	v_mul_f32_dpp v210, v210, v210 row_shr:4 row_mask:0xf bank_mask:0xf
	v_mul_f32_dpp v216, v216, v216 row_shr:4 row_mask:0xf bank_mask:0xf
	v_fmac_f32_dpp v167, v167, v166 row_shr:8 row_mask:0xf bank_mask:0xf bound_ctrl:1
	v_fmac_f32_dpp v205, v205, v204 row_shr:8 row_mask:0xf bank_mask:0xf bound_ctrl:1
	v_fmac_f32_dpp v211, v211, v210 row_shr:8 row_mask:0xf bank_mask:0xf bound_ctrl:1
	v_fmac_f32_dpp v217, v217, v216 row_shr:8 row_mask:0xf bank_mask:0xf bound_ctrl:1
	v_mul_f32_dpp v166, v166, v166 row_shr:8 row_mask:0xf bank_mask:0xf
	v_mul_f32_dpp v204, v204, v204 row_shr:8 row_mask:0xf bank_mask:0xf
	v_mul_f32_dpp v210, v210, v210 row_shr:8 row_mask:0xf bank_mask:0xf
	v_mul_f32_dpp v216, v216, v216 row_shr:8 row_mask:0xf bank_mask:0xf
	v_fma_f32 v168, v166, v12, v167
	v_fma_f32 v206, v204, v13, v205
	v_fma_f32 v212, v210, v14, v211
	v_fma_f32 v218, v216, v15, v217
	ds_bpermute_b32 v12, v232, v168
	ds_bpermute_b32 v13, v232, v206
	ds_bpermute_b32 v14, v232, v212
	ds_bpermute_b32 v15, v232, v218
	s_waitcnt vmcnt(21)
	v_lshlrev_b32_e32 v169, 16, v30
	v_and_b32_e32 v207, 0xffff0000, v30
	v_lshlrev_b32_e32 v213, 16, v31
	v_and_b32_e32 v219, 0xffff0000, v31
	v_mul_f32_e32 v170, v169, v169
	v_mul_f32_e32 v208, v207, v207
	v_mul_f32_e32 v214, v213, v213
	v_mul_f32_e32 v220, v219, v219
	v_fmaak_f32 v170, v170, v249, 0xc0135761
	v_fmaak_f32 v208, v208, v249, 0xc0135761
	v_fmaak_f32 v214, v214, v249, 0xc0135761
	v_fmaak_f32 v220, v220, v249, 0xc0135761
	v_mul_f32_e32 v170, v169, v170
	v_mul_f32_e32 v208, v207, v208
	v_mul_f32_e32 v214, v213, v214
	v_mul_f32_e32 v220, v219, v220
	v_exp_f32_e32 v170, v170
	v_exp_f32_e32 v208, v208
	v_exp_f32_e32 v214, v214
	v_exp_f32_e32 v220, v220
	v_add_f32_e32 v170, 1.0, v170
	v_add_f32_e32 v208, 1.0, v208
	v_add_f32_e32 v214, 1.0, v214
	v_add_f32_e32 v220, 1.0, v220
	v_rcp_f32_e32 v170, v170
	v_rcp_f32_e32 v208, v208
	v_rcp_f32_e32 v214, v214
	v_rcp_f32_e32 v220, v220
	v_mul_f32_e32 v170, v169, v170
	v_mul_f32_e32 v208, v207, v208
	v_mul_f32_e32 v214, v213, v214
	v_mul_f32_e32 v220, v219, v220
	v_mul_f32_e32 v170, v170, v168
	v_mul_f32_e32 v208, v208, v206
	v_mul_f32_e32 v214, v214, v212
	v_mul_f32_e32 v220, v220, v218
	v_cvt_pk_bf16_f32 v242, v170, v208
	v_cvt_pk_bf16_f32 v243, v214, v220
	global_store_dwordx2 v236, v[242:243], s[100:101] offset:96
	ds_read_b128 v[110:113], v229 offset:16640
	ds_read_b128 v[122:125], v229 offset:36608
	ds_read_b128 v[114:117], v229 offset:16704
	ds_read_b128 v[126:129], v229 offset:36672
	ds_read_b128 v[118:121], v229 offset:16768
	ds_read_b128 v[130:133], v229 offset:36736
	v_fmamk_f32 v166, v134, 0xbfb8aa3b, v150
	v_fmamk_f32 v204, v135, 0xbfb8aa3b, v151
	v_fmamk_f32 v210, v136, 0xbfb8aa3b, v152
	v_fmamk_f32 v216, v137, 0xbfb8aa3b, v153
	v_fmamk_f32 v167, v138, 0xbfb8aa3b, v154
	v_fmamk_f32 v205, v139, 0xbfb8aa3b, v155
	v_fmamk_f32 v211, v140, 0xbfb8aa3b, v156
	v_fmamk_f32 v217, v141, 0xbfb8aa3b, v157
	v_exp_f32_e32 v166, v166
	v_exp_f32_e32 v204, v204
	v_exp_f32_e32 v210, v210
	v_exp_f32_e32 v216, v216
	v_exp_f32_e32 v167, v167
	v_exp_f32_e32 v205, v205
	v_exp_f32_e32 v211, v211
	v_exp_f32_e32 v217, v217
	v_add_f32_e32 v166, 1.0, v166
	v_add_f32_e32 v204, 1.0, v204
	v_add_f32_e32 v210, 1.0, v210
	v_add_f32_e32 v216, 1.0, v216
	v_add_f32_e32 v167, 1.0, v167
	v_add_f32_e32 v205, 1.0, v205
	v_add_f32_e32 v211, 1.0, v211
	v_add_f32_e32 v217, 1.0, v217
	v_rcp_f32_e32 v166, v166
	v_rcp_f32_e32 v204, v204
	v_rcp_f32_e32 v210, v210
	v_rcp_f32_e32 v216, v216
	v_rcp_f32_e32 v167, v167
	v_rcp_f32_e32 v205, v205
	v_rcp_f32_e32 v211, v211
	v_rcp_f32_e32 v217, v217
	v_mul_f32_e32 v168, v158, v166
	v_mul_f32_e32 v206, v159, v204
	v_mul_f32_e32 v212, v160, v210
	v_mul_f32_e32 v218, v161, v216
	v_mul_f32_e32 v167, v162, v167
	v_mul_f32_e32 v205, v163, v205
	v_mul_f32_e32 v211, v164, v211
	v_mul_f32_e32 v217, v165, v217
	ds_read_b128 v[150:153], v230 offset:320
	ds_read_b128 v[154:157], v230 offset:704
	ds_read_b128 v[158:161], v230 offset:1088
	ds_read_b128 v[162:165], v231 offset:320
	v_exp_f32_e32 v166, v168
	v_exp_f32_e32 v204, v206
	v_exp_f32_e32 v210, v212
	v_exp_f32_e32 v216, v218
	v_fmaak_f32 v170, v168, v248, 0xbe1d955b
	v_fmaak_f32 v208, v206, v248, 0xbe1d955b
	v_fmaak_f32 v214, v212, v248, 0xbe1d955b
	v_fmaak_f32 v220, v218, v248, 0xbe1d955b
	v_fmaak_f32 v170, v168, v170, 0xbee35847
	v_fmaak_f32 v208, v206, v208, 0xbee35847
	v_fmaak_f32 v214, v212, v214, 0xbee35847
	v_fmaak_f32 v220, v218, v220, 0xbee35847
	v_min3_f32 v169, v168, v206, v212
	v_fmaak_f32 v170, v168, v170, 0xbf75fdf0
	v_fmaak_f32 v208, v206, v208, 0xbf75fdf0
	v_fmaak_f32 v214, v212, v214, 0xbf75fdf0
	v_fmaak_f32 v220, v218, v220, 0xbf75fdf0
	v_min_f32_e32 v169, v169, v218
	v_fmaak_f32 v170, v168, v170, 0xbfb17218
	v_fmaak_f32 v208, v206, v208, 0xbfb17218
	v_fmaak_f32 v214, v212, v214, 0xbfb17218
	v_fmaak_f32 v220, v218, v220, 0xbfb17218
	v_cmp_nlt_f32_e32 vcc, 0xbe38aa3b, v169
	v_mul_f32_e32 v170, v170, v168
	v_mul_f32_e32 v208, v208, v206
	v_mul_f32_e32 v214, v214, v212
	v_mul_f32_e32 v220, v220, v218
	s_cbranch_vccnz .Lscan2_far4
.Lscan2_back4:
	v_sqrt_f32_e32 v170, v170
	v_sqrt_f32_e32 v208, v208
	v_sqrt_f32_e32 v214, v214
	v_sqrt_f32_e32 v220, v220
	v_mul_f32_e32 v167, v167, v170
	v_mul_f32_e32 v205, v205, v208
	v_mul_f32_e32 v211, v211, v214
	v_mul_f32_e32 v217, v217, v220
	s_waitcnt lgkmcnt(0)
	v_mfma_f32_16x16x32_bf16 v[142:145], v[110:113], v[98:101], 0
	v_mfma_f32_16x16x32_bf16 v[146:149], v[122:125], v[98:101], 0
	v_mfma_f32_16x16x32_bf16 v[142:145], v[114:117], v[102:105], v[142:145]
	v_mfma_f32_16x16x32_bf16 v[146:149], v[126:129], v[102:105], v[146:149]
	v_mfma_f32_16x16x32_bf16 v[142:145], v[118:121], v[106:109], v[142:145]
	v_mfma_f32_16x16x32_bf16 v[146:149], v[130:133], v[106:109], v[146:149]
	v_fmac_f32_dpp v167, v167, v166 row_shr:1 row_mask:0xf bank_mask:0xf bound_ctrl:1
	v_fmac_f32_dpp v205, v205, v204 row_shr:1 row_mask:0xf bank_mask:0xf bound_ctrl:1
	v_fmac_f32_dpp v211, v211, v210 row_shr:1 row_mask:0xf bank_mask:0xf bound_ctrl:1
	v_fmac_f32_dpp v217, v217, v216 row_shr:1 row_mask:0xf bank_mask:0xf bound_ctrl:1
	v_mul_f32_dpp v166, v166, v166 row_shr:1 row_mask:0xf bank_mask:0xf
	v_mul_f32_dpp v204, v204, v204 row_shr:1 row_mask:0xf bank_mask:0xf
	v_mul_f32_dpp v210, v210, v210 row_shr:1 row_mask:0xf bank_mask:0xf
	v_mul_f32_dpp v216, v216, v216 row_shr:1 row_mask:0xf bank_mask:0xf
	v_fmac_f32_dpp v167, v167, v166 row_shr:2 row_mask:0xf bank_mask:0xf bound_ctrl:1
	v_fmac_f32_dpp v205, v205, v204 row_shr:2 row_mask:0xf bank_mask:0xf bound_ctrl:1
	v_fmac_f32_dpp v211, v211, v210 row_shr:2 row_mask:0xf bank_mask:0xf bound_ctrl:1
	v_fmac_f32_dpp v217, v217, v216 row_shr:2 row_mask:0xf bank_mask:0xf bound_ctrl:1
	v_mul_f32_dpp v166, v166, v166 row_shr:2 row_mask:0xf bank_mask:0xf
	v_mul_f32_dpp v204, v204, v204 row_shr:2 row_mask:0xf bank_mask:0xf
	v_mul_f32_dpp v210, v210, v210 row_shr:2 row_mask:0xf bank_mask:0xf
	v_mul_f32_dpp v216, v216, v216 row_shr:2 row_mask:0xf bank_mask:0xf
	v_fmac_f32_dpp v167, v167, v166 row_shr:4 row_mask:0xf bank_mask:0xf bound_ctrl:1
	v_fmac_f32_dpp v205, v205, v204 row_shr:4 row_mask:0xf bank_mask:0xf bound_ctrl:1
	v_fmac_f32_dpp v211, v211, v210 row_shr:4 row_mask:0xf bank_mask:0xf bound_ctrl:1
	v_fmac_f32_dpp v217, v217, v216 row_shr:4 row_mask:0xf bank_mask:0xf bound_ctrl:1
	v_mul_f32_dpp v166, v166, v166 row_shr:4 row_mask:0xf bank_mask:0xf
	v_mul_f32_dpp v204, v204, v204 row_shr:4 row_mask:0xf bank_mask:0xf
	v_mul_f32_dpp v210, v210, v210 row_shr:4 row_mask:0xf bank_mask:0xf
	v_mul_f32_dpp v216, v216, v216 row_shr:4 row_mask:0xf bank_mask:0xf
	v_fmac_f32_dpp v167, v167, v166 row_shr:8 row_mask:0xf bank_mask:0xf bound_ctrl:1
	v_fmac_f32_dpp v205, v205, v204 row_shr:8 row_mask:0xf bank_mask:0xf bound_ctrl:1
	v_fmac_f32_dpp v211, v211, v210 row_shr:8 row_mask:0xf bank_mask:0xf bound_ctrl:1
	v_fmac_f32_dpp v217, v217, v216 row_shr:8 row_mask:0xf bank_mask:0xf bound_ctrl:1
	v_mul_f32_dpp v166, v166, v166 row_shr:8 row_mask:0xf bank_mask:0xf
	v_mul_f32_dpp v204, v204, v204 row_shr:8 row_mask:0xf bank_mask:0xf
	v_mul_f32_dpp v210, v210, v210 row_shr:8 row_mask:0xf bank_mask:0xf
	v_mul_f32_dpp v216, v216, v216 row_shr:8 row_mask:0xf bank_mask:0xf
	v_fma_f32 v168, v166, v16, v167
	v_fma_f32 v206, v204, v17, v205
	v_fma_f32 v212, v210, v18, v211
	v_fma_f32 v218, v216, v19, v217
	ds_bpermute_b32 v16, v232, v168
	ds_bpermute_b32 v17, v232, v206
	ds_bpermute_b32 v18, v232, v212
	ds_bpermute_b32 v19, v232, v218
	s_waitcnt vmcnt(21)
	v_lshlrev_b32_e32 v169, 16, v32
	v_and_b32_e32 v207, 0xffff0000, v32
	v_lshlrev_b32_e32 v213, 16, v33
	v_and_b32_e32 v219, 0xffff0000, v33
	v_mul_f32_e32 v170, v169, v169
	v_mul_f32_e32 v208, v207, v207
	v_mul_f32_e32 v214, v213, v213
	v_mul_f32_e32 v220, v219, v219
	v_fmaak_f32 v170, v170, v249, 0xc0135761
	v_fmaak_f32 v208, v208, v249, 0xc0135761
	v_fmaak_f32 v214, v214, v249, 0xc0135761
	v_fmaak_f32 v220, v220, v249, 0xc0135761
	v_mul_f32_e32 v170, v169, v170
	v_mul_f32_e32 v208, v207, v208
	v_mul_f32_e32 v214, v213, v214
	v_mul_f32_e32 v220, v219, v220
	v_exp_f32_e32 v170, v170
	v_exp_f32_e32 v208, v208
	v_exp_f32_e32 v214, v214
	v_exp_f32_e32 v220, v220
	v_add_f32_e32 v170, 1.0, v170
	v_add_f32_e32 v208, 1.0, v208
	v_add_f32_e32 v214, 1.0, v214
	v_add_f32_e32 v220, 1.0, v220
	v_rcp_f32_e32 v170, v170
	v_rcp_f32_e32 v208, v208
	v_rcp_f32_e32 v214, v214
	v_rcp_f32_e32 v220, v220
	v_mul_f32_e32 v170, v169, v170
	v_mul_f32_e32 v208, v207, v208
	v_mul_f32_e32 v214, v213, v214
	v_mul_f32_e32 v220, v219, v220
	v_mul_f32_e32 v170, v170, v168
	v_mul_f32_e32 v208, v208, v206
	v_mul_f32_e32 v214, v214, v212
	v_mul_f32_e32 v220, v220, v218
	v_cvt_pk_bf16_f32 v242, v170, v208
	v_cvt_pk_bf16_f32 v243, v214, v220
	global_store_dwordx2 v236, v[242:243], s[100:101] offset:128
	v_fmamk_f32 v166, v142, 0xbfb8aa3b, v150
	v_fmamk_f32 v204, v143, 0xbfb8aa3b, v151
	v_fmamk_f32 v210, v144, 0xbfb8aa3b, v152
	v_fmamk_f32 v216, v145, 0xbfb8aa3b, v153
	v_fmamk_f32 v167, v146, 0xbfb8aa3b, v154
	v_fmamk_f32 v205, v147, 0xbfb8aa3b, v155
	v_fmamk_f32 v211, v148, 0xbfb8aa3b, v156
	v_fmamk_f32 v217, v149, 0xbfb8aa3b, v157
	v_exp_f32_e32 v166, v166
	v_exp_f32_e32 v204, v204
	v_exp_f32_e32 v210, v210
	v_exp_f32_e32 v216, v216
	v_exp_f32_e32 v167, v167
	v_exp_f32_e32 v205, v205
	v_exp_f32_e32 v211, v211
	v_exp_f32_e32 v217, v217
	v_add_f32_e32 v166, 1.0, v166
	v_add_f32_e32 v204, 1.0, v204
	v_add_f32_e32 v210, 1.0, v210
	v_add_f32_e32 v216, 1.0, v216
	v_add_f32_e32 v167, 1.0, v167
	v_add_f32_e32 v205, 1.0, v205
	v_add_f32_e32 v211, 1.0, v211
	v_add_f32_e32 v217, 1.0, v217
	v_rcp_f32_e32 v166, v166
	v_rcp_f32_e32 v204, v204
	v_rcp_f32_e32 v210, v210
	v_rcp_f32_e32 v216, v216
	v_rcp_f32_e32 v167, v167
	v_rcp_f32_e32 v205, v205
	v_rcp_f32_e32 v211, v211
	v_rcp_f32_e32 v217, v217
	v_mul_f32_e32 v168, v158, v166
	v_mul_f32_e32 v206, v159, v204
	v_mul_f32_e32 v212, v160, v210
	v_mul_f32_e32 v218, v161, v216
	v_mul_f32_e32 v167, v162, v167
	v_mul_f32_e32 v205, v163, v205
	v_mul_f32_e32 v211, v164, v211
	v_mul_f32_e32 v217, v165, v217
	v_exp_f32_e32 v166, v168
	v_exp_f32_e32 v204, v206
	v_exp_f32_e32 v210, v212
	v_exp_f32_e32 v216, v218
	v_fmaak_f32 v170, v168, v248, 0xbe1d955b
	v_fmaak_f32 v208, v206, v248, 0xbe1d955b
	v_fmaak_f32 v214, v212, v248, 0xbe1d955b
	v_fmaak_f32 v220, v218, v248, 0xbe1d955b
	v_fmaak_f32 v170, v168, v170, 0xbee35847
	v_fmaak_f32 v208, v206, v208, 0xbee35847
	v_fmaak_f32 v214, v212, v214, 0xbee35847
	v_fmaak_f32 v220, v218, v220, 0xbee35847
	v_min3_f32 v169, v168, v206, v212
	v_fmaak_f32 v170, v168, v170, 0xbf75fdf0
	v_fmaak_f32 v208, v206, v208, 0xbf75fdf0
	v_fmaak_f32 v214, v212, v214, 0xbf75fdf0
	v_fmaak_f32 v220, v218, v220, 0xbf75fdf0
	v_min_f32_e32 v169, v169, v218
	v_fmaak_f32 v170, v168, v170, 0xbfb17218
	v_fmaak_f32 v208, v206, v208, 0xbfb17218
	v_fmaak_f32 v214, v212, v214, 0xbfb17218
	v_fmaak_f32 v220, v218, v220, 0xbfb17218
	v_cmp_nlt_f32_e32 vcc, 0xbe38aa3b, v169
	v_mul_f32_e32 v170, v170, v168
	v_mul_f32_e32 v208, v208, v206
	v_mul_f32_e32 v214, v214, v212
	v_mul_f32_e32 v220, v220, v218
	s_cbranch_vccnz .Lscan2_far5
